# attention: softmax reference = static Cauchy-Schwarz score bound (no running max / rescale branch); role-based s_setprio (MFMA part prio 1, softmax part prio 0) on top of the half-tile stagger
# speedup vs baseline: 1.0214x; 1.0108x over previous
.LBB0_330:
	s_cmpk_gt_i32 s2, 0x7ff
	s_cbranch_scc1 .LBB0_376
	v_mbcnt_lo_u32_b32 v0, -1, 0
	v_mbcnt_hi_u32_b32 v0, -1, v0
	v_lshlrev_b32_e32 v1, 2, v0
	v_and_b32_e32 v2, 31, v0
	v_lshlrev_b32_e32 v2, 2, v2
	v_add_u32_e32 v2, 0x100, v2
	v_readlane_b32 s0, v242, 15
	v_readlane_b32 s1, v242, 16
	v_readlane_b32 s40, v242, 17
	v_readlane_b32 s41, v242, 18
	v_readlane_b32 s46, v242, 19
	v_readlane_b32 s47, v242, 20
	v_readlane_b32 s96, v242, 21
	v_readlane_b32 s97, v242, 22
	s_nop 4
	global_load_dword v3, v1, s[0:1]
	global_load_dword v4, v2, s[0:1]
	global_load_dword v5, v1, s[40:41]
	global_load_dword v6, v2, s[40:41]
	global_load_dword v7, v1, s[46:47]
	global_load_dword v8, v1, s[96:97]
	s_waitcnt vmcnt(0)
	v_max3_f32 v3, |v3|, |v4|, |v5|
	v_max3_f32 v6, |v6|, |v7|, |v8|
	v_max_f32_e32 v3, v3, v6
	v_xor_b32_e32 v4, 4, v1
	ds_bpermute_b32 v5, v4, v3
	s_waitcnt lgkmcnt(0)
	v_max_f32_e32 v3, v3, v5
	v_xor_b32_e32 v4, 8, v1
	ds_bpermute_b32 v5, v4, v3
	s_waitcnt lgkmcnt(0)
	v_max_f32_e32 v3, v3, v5
	v_xor_b32_e32 v4, 16, v1
	ds_bpermute_b32 v5, v4, v3
	s_waitcnt lgkmcnt(0)
	v_max_f32_e32 v3, v3, v5
	v_xor_b32_e32 v4, 32, v1
	ds_bpermute_b32 v5, v4, v3
	s_waitcnt lgkmcnt(0)
	v_max_f32_e32 v3, v3, v5
	v_xor_b32_e32 v4, 64, v1
	ds_bpermute_b32 v5, v4, v3
	s_waitcnt lgkmcnt(0)
	v_max_f32_e32 v3, v3, v5
	v_xor_b32_e32 v4, 128, v1
	ds_bpermute_b32 v5, v4, v3
	s_waitcnt lgkmcnt(0)
	v_max_f32_e32 v3, v3, v5
	v_mul_f32_e32 v3, v3, v3
	v_mul_f32_e32 v4, 0x413c5bb7, v3
	v_mul_f32_e32 v5, 0x4166b0d9, v3
	s_nop 0
	v_readfirstlane_b32 s99, v4
	v_readfirstlane_b32 s100, v5
	s_lshl_b32 s0, s2, 5
	s_and_b32 s0, s0, 0x400
	s_cmpk_eq_i32 s30, 0x100
	s_cselect_b32 s46, s0, 0x100
	s_add_u32 s47, s26, 0xc000000
	s_addc_u32 s70, s27, 0
	s_add_u32 s96, s26, 0x17000000
	s_addc_u32 s97, s27, 0
	s_add_u32 s40, s26, 0x11000000
	s_addc_u32 s41, s27, 0
	s_add_u32 s92, s26, 0x1a000000
	s_addc_u32 s93, s27, 0
	s_add_u32 s66, s26, 0x13000000
	s_addc_u32 s67, s27, 0
	v_writelane_b32 v242, s4, 39
	s_add_u32 s69, s26, 0x1a800000
	s_addc_u32 s10, s27, 0
	v_writelane_b32 v242, s5, 40
	v_lshrrev_b32_e32 v3, 3, v168
	v_lshlrev_b32_e32 v0, 4, v168
	v_writelane_b32 v242, s82, 37
	s_add_u32 s11, s26, 0x90000
	v_and_b32_e32 v1, 0x70, v0
	v_and_b32_e32 v5, 0x60, v0
	v_lshlrev_b32_e32 v4, 3, v168
	v_mul_u32_u24_e32 v8, 0x90, v3
	v_writelane_b32 v242, s83, 38
	s_addc_u32 s0, s27, 0
	v_and_b32_e32 v6, 8, v4
	v_add3_u32 v177, v8, v1, 0
	v_add_u32_e32 v1, 0, v5
	v_add_u32_e32 v5, 0x200, v168
	v_writelane_b32 v242, s0, 36
	v_add3_u32 v198, v1, v6, v8
	v_mul_u32_u24_e32 v6, 0x1556, v5
	v_and_b32_e32 v170, 31, v168
	v_lshrrev_b32_e32 v171, 5, v169
	v_readlane_b32 s0, v242, 33
	v_mul_u32_u24_e32 v1, 0x1556, v168
	v_lshrrev_b32_e32 v6, 16, v6
	s_lshl_b32 s14, s0, 5
	v_lshlrev_b32_e32 v7, 4, v171
	v_lshrrev_b32_e32 v1, 16, v1
	v_add_lshl_u32 v206, v5, v6, 4
	v_mul_u32_u24_e32 v5, 0xd0, v170
	v_mov_b32_e32 v173, 0
	s_add_u32 s0, s26, 0x70000
	v_add_lshl_u32 v207, v168, v1, 4
	v_add3_u32 v208, 0, v5, v7
	v_lshlrev_b32_e32 v1, 6, v170
	v_and_b32_e32 v5, 7, v168
	s_movk_i32 s1, 0x100
	v_or_b32_e32 v172, s14, v170
	v_writelane_b32 v242, s0, 33
	s_addc_u32 s0, s27, 0
	v_sub_u32_e32 v209, v208, v1
	v_mov_b32_e32 v1, v173
	v_lshlrev_b32_e32 v5, 4, v5
	v_mul_u32_u24_e32 v9, 0x90, v170
	v_lshlrev_b64 v[174:175], 11, v[172:173]
	v_writelane_b32 v242, s0, 34
	v_cmp_gt_u32_e64 s[4:5], s1, v168
	v_lshl_add_u64 v[0:1], s[26:27], 0, v[0:1]
	s_mov_b64 s[0:1], 0x1a006000
	v_lshl_or_b32 v172, v3, 16, v5
	v_add3_u32 v199, v7, v9, 0
	v_lshl_add_u64 v[178:179], v[0:1], 0, s[0:1]
	v_lshl_add_u64 v[6:7], s[26:27], 0, v[172:173]
	s_mov_b64 s[0:1], 0x13000180
	v_lshl_add_u64 v[180:181], v[6:7], 0, s[0:1]
	s_mov_b64 s[0:1], 0x1700b000
	v_cmp_gt_u32_e64 s[6:7], 32, v169
	v_exp_f32_e32 v169, 0xbfd49a78
	v_exp_f32_e32 v200, 0xc0549a78
	v_exp_f32_e32 v201, 0xc09f73da
	v_exp_f32_e32 v202, 0xc0d49a78
	v_exp_f32_e32 v203, 0xc104e08b
	v_exp_f32_e32 v204, 0xc11f73da
	v_exp_f32_e32 v205, 0xc13a0729
	v_lshl_add_u64 v[182:183], v[0:1], 0, s[0:1]
	v_mbcnt_lo_u32_b32 v0, -1, 0
	v_mbcnt_hi_u32_b32 v212, -1, v0
	v_lshlrev_b32_e32 v2, 15, v3
	s_mov_b32 s17, 0
	v_and_b32_e32 v4, 56, v4
	s_mov_b64 s[0:1], 0x11000180
	v_and_b32_e32 v0, 64, v212
	s_mov_b32 s15, s17
	v_lshlrev_b32_e32 v176, 3, v171
	v_lshl_add_u64 v[184:185], v[6:7], 0, s[0:1]
	v_mov_b32_e32 v210, 0x358637bd
	s_mov_b32 s64, 0xf800000
	v_mov_b32_e32 v211, 0x260
	s_mov_b32 s65, 0x3e38aa3b
	s_mov_b32 s68, 0x41000000
	s_mov_b64 s[20:21], 0x2000
	s_mov_b64 s[22:23], 0x80
	s_mov_b32 s71, 0x3e16c740
	s_mov_b64 s[36:37], 0x3000
	v_xor_b32_e32 v213, 32, v212
	v_add_u32_e32 v214, 64, v0
	v_lshlrev_b32_e32 v172, 1, v2
	v_lshlrev_b32_e32 v186, 1, v4
	v_lshlrev_b32_e32 v188, 4, v168
	v_add_u32_e32 v215, 0x4800, v198
	v_add_u32_e32 v216, 0x6800, v198
	v_mov_b32_e32 v217, 0x60000
	s_branch .LBB0_334

.LBB0_334:
	s_lshr_b32 s3, s2, 3
	s_lshl_b32 s0, s2, 6
	s_bfe_u32 s72, s2, 0x30003
	s_and_b32 s73, s0, 0xf000
	s_xor_b32 s8, s2, s46
	s_and_b32 s0, s2, 7
	s_bfe_u32 s1, s3, 0x40003
	s_cmpk_gt_u32 s8, 0x3ff
	s_mov_b64 s[42:43], -1
	s_cbranch_scc0 .LBB0_347
	s_lshl_b32 s3, s3, 16
	s_and_b32 s8, s3, 0x40000
	s_and_b32 s3, s3, 0x780000
	s_or_b32 s16, s3, s8
	s_lshl_b32 s3, s72, 20
	s_and_b32 s3, s3, 0x400000
	v_lshl_add_u64 v[190:191], v[178:179], 0, s[16:17]
	s_or_b32 s16, s73, s3
	s_lshl_b32 s75, s1, 11
	s_lshl_b32 s74, s0, 8
	v_lshl_add_u64 v[192:193], v[180:181], 0, s[16:17]
	s_or_b32 s16, s75, s74
	s_lshr_b32 s18, s72, 2
	s_mul_i32 s3, s16, 0xc00
	s_add_u32 s8, s26, s3
	s_addc_u32 s9, s27, 0
	s_lshl_b32 s3, s72, 6
	s_lshl_b32 s19, s72, 7
	s_add_u32 s8, s8, s19
	s_addc_u32 s9, s9, 0
	s_add_u32 s8, s8, 0x6000540
	s_addc_u32 s9, s9, 0
	s_lshl_b32 s19, s1, 19
	s_lshl_b32 s33, s18, 18
	s_or_b32 s19, s19, s33
	s_add_u32 s42, s92, s19
	s_addc_u32 s43, s93, 0
	s_lshl_b32 s18, s18, 22
	v_mov_b32_e32 v0, v170
	v_mov_b32_e32 v2, v171
	s_add_u32 s18, s66, s18
	s_addc_u32 s19, s67, 0
	s_lshl_b32 s33, s1, 12
	v_add_u32_e32 v3, s14, v0
	v_readlane_b32 s48, v242, 17
	v_mov_b64_e32 v[0:1], s[8:9]
	s_movk_i32 s8, 0xc00
	v_lshlrev_b32_e32 v4, 3, v2
	s_add_u32 s44, s18, s33
	v_readlane_b32 s50, v242, 19
	v_readlane_b32 s51, v242, 20
	v_mad_i64_i32 v[0:1], s[8:9], v3, s8, v[0:1]
	v_ashrrev_i32_e32 v5, 31, v4
	s_addc_u32 s45, s19, 0
	s_mov_b64 s[18:19], s[50:51]
	v_lshl_add_u64 v[0:1], v[4:5], 1, v[0:1]
	global_load_dwordx4 v[38:41], v[0:1], off
	global_load_dwordx4 v[42:45], v[0:1], off offset:32
	global_load_dwordx4 v[46:49], v[0:1], off offset:64
	global_load_dwordx4 v[50:53], v[0:1], off offset:96
	v_cmp_lt_i32_e32 vcc, v213, v214
	v_add_u32_e32 v0, s74, v3
	v_ashrrev_i32_e32 v0, 6, v0
	v_cndmask_b32_e32 v1, v212, v213, vcc
	v_lshlrev_b32_e32 v218, 2, v1
	v_cvt_f32_i32_e32 v1, v4
	v_cvt_f32_i32_e32 v6, v0
	v_and_b32_e32 v0, 63, v3
	v_cvt_f32_ubyte0_e32 v110, v0
	v_mul_f32_e32 v0, 0xbf549a78, v1
	v_exp_f32_e32 v7, v0
	v_or_b32_e32 v0, 1, v4
	v_cvt_f32_i32_e32 v1, v0
	v_lshl_add_u64 v[32:33], v[4:5], 2, s[18:19]
	v_mul_f32_e32 v0, v7, v6
	v_mul_f32_e32 v2, 0.15915494, v0
	v_mul_f32_e32 v1, 0xbf549a78, v1
	v_exp_f32_e32 v5, v1
	v_or_b32_e32 v1, 2, v4
	v_cvt_f32_i32_e32 v3, v1
	v_cos_f32_e32 v0, v2
	v_mul_f32_e32 v1, v5, v6
	v_mul_f32_e32 v8, 0.15915494, v1
	v_mul_f32_e32 v3, 0xbf549a78, v3
	v_cos_f32_e32 v1, v8
	v_exp_f32_e32 v10, v3
	v_sin_f32_e32 v3, v8
	v_or_b32_e32 v8, 3, v4
	v_cvt_f32_i32_e32 v9, v8
	v_mul_f32_e32 v8, v10, v6
	v_mul_f32_e32 v11, 0.15915494, v8
	v_cos_f32_e32 v8, v11
	v_mul_f32_e32 v9, 0xbf549a78, v9
	v_exp_f32_e32 v13, v9
	v_or_b32_e32 v9, 4, v4
	v_sin_f32_e32 v14, v11
	v_cvt_f32_i32_e32 v11, v9
	v_mul_f32_e32 v9, v13, v6
	v_mul_f32_e32 v12, 0.15915494, v9
	v_cos_f32_e32 v9, v12
	v_mul_f32_e32 v11, 0xbf549a78, v11
	v_exp_f32_e32 v20, v11
	v_or_b32_e32 v11, 5, v4
	v_cvt_f32_i32_e32 v11, v11
	v_sin_f32_e32 v15, v12
	v_mul_f32_e32 v12, v20, v6
	v_mul_f32_e32 v12, 0.15915494, v12
	v_mul_f32_e32 v11, 0xbf549a78, v11
	v_exp_f32_e32 v21, v11
	v_or_b32_e32 v11, 6, v4
	v_cvt_f32_i32_e32 v11, v11
	v_or_b32_e32 v4, 7, v4
	v_cvt_f32_i32_e32 v4, v4
	v_cos_f32_e32 v22, v12
	v_mul_f32_e32 v11, 0xbf549a78, v11
	v_exp_f32_e32 v24, v11
	v_mul_f32_e32 v4, 0xbf549a78, v4
	v_exp_f32_e32 v111, v4
	v_sin_f32_e32 v26, v12
	v_mul_f32_e32 v11, v24, v6
	v_mul_f32_e32 v4, 0.15915494, v11
	v_cos_f32_e32 v28, v4
	v_sin_f32_e32 v30, v4
	v_mul_f32_e32 v4, v111, v6
	v_mul_f32_e32 v4, 0.15915494, v4
	v_cos_f32_e32 v29, v4
	v_sin_f32_e32 v31, v4
	v_mul_f32_e32 v4, v7, v110
	v_mul_f32_e32 v4, 0.15915494, v4
	v_cos_f32_e32 v16, v4
	v_sin_f32_e32 v18, v4
	v_mul_f32_e32 v4, v5, v110
	v_mul_f32_e32 v4, 0.15915494, v4
	v_mul_f32_e32 v12, v21, v6
	v_cos_f32_e32 v17, v4
	v_sin_f32_e32 v19, v4
	s_waitcnt vmcnt(0)
	v_lshlrev_b32_e32 v106, 16, v38
	v_and_b32_e32 v107, 0xffff0000, v38
	v_lshlrev_b32_e32 v98, 16, v39
	v_and_b32_e32 v99, 0xffff0000, v39
	v_pk_mul_f32 v[38:39], v[106:107], v[106:107]
	v_pk_mul_f32 v[100:101], v[98:99], v[98:99]
	v_add_f32_e32 v38, v38, v39
	v_lshlrev_b32_e32 v92, 16, v40
	v_and_b32_e32 v93, 0xffff0000, v40
	v_add_f32_e32 v38, v100, v38
	v_lshlrev_b32_e32 v82, 16, v41
	v_and_b32_e32 v83, 0xffff0000, v41
	v_pk_mul_f32 v[40:41], v[92:93], v[92:93]
	v_add_f32_e32 v38, v101, v38
	v_add_f32_e32 v38, v40, v38
	v_pk_mul_f32 v[84:85], v[82:83], v[82:83]
	v_add_f32_e32 v38, v41, v38
	v_lshlrev_b32_e32 v108, 16, v42
	v_and_b32_e32 v109, 0xffff0000, v42
	v_add_f32_e32 v38, v84, v38
	v_lshlrev_b32_e32 v102, 16, v43
	v_and_b32_e32 v103, 0xffff0000, v43
	v_pk_mul_f32 v[42:43], v[108:109], v[108:109]
	v_add_f32_e32 v38, v85, v38
	v_add_f32_e32 v38, v42, v38
	v_pk_mul_f32 v[104:105], v[102:103], v[102:103]
	v_add_f32_e32 v38, v43, v38
	v_lshlrev_b32_e32 v94, 16, v44
	v_and_b32_e32 v95, 0xffff0000, v44
	v_add_f32_e32 v38, v104, v38
	v_pk_mul_f32 v[96:97], v[94:95], v[94:95]
	v_add_f32_e32 v38, v105, v38
	v_mul_f32_e32 v4, v10, v110
	v_lshlrev_b32_e32 v86, 16, v45
	v_and_b32_e32 v87, 0xffff0000, v45
	v_add_f32_e32 v38, v96, v38
	v_mul_f32_e32 v12, 0.15915494, v12
	v_mul_f32_e32 v4, 0.15915494, v4
	v_pk_mul_f32 v[90:91], v[86:87], v[86:87]
	v_add_f32_e32 v38, v97, v38
	v_cos_f32_e32 v23, v12
	v_sin_f32_e32 v27, v12
	v_cos_f32_e32 v10, v4
	v_sin_f32_e32 v12, v4
	v_mul_f32_e32 v4, v13, v110
	v_lshlrev_b32_e32 v76, 16, v46
	v_and_b32_e32 v77, 0xffff0000, v46
	v_add_f32_e32 v38, v90, v38
	v_mul_f32_e32 v4, 0.15915494, v4
	v_pk_mul_f32 v[78:79], v[76:77], v[76:77]
	v_add_f32_e32 v38, v91, v38
	v_cos_f32_e32 v11, v4
	v_sin_f32_e32 v13, v4
	v_mul_f32_e32 v4, v20, v110
	v_lshlrev_b32_e32 v72, 16, v47
	v_and_b32_e32 v73, 0xffff0000, v47
	v_add_f32_e32 v38, v78, v38
	v_mul_f32_e32 v5, 0.15915494, v4
	v_mul_f32_e32 v20, v24, v110
	v_pk_mul_f32 v[68:69], v[72:73], v[72:73]
	v_add_f32_e32 v38, v79, v38
	v_cos_f32_e32 v4, v5
	v_sin_f32_e32 v6, v5
	v_mul_f32_e32 v5, v21, v110
	v_mul_f32_e32 v112, 0.15915494, v20
	v_lshlrev_b32_e32 v20, 16, v49
	v_and_b32_e32 v21, 0xffff0000, v49
	v_lshlrev_b32_e32 v24, 16, v53
	v_and_b32_e32 v25, 0xffff0000, v53
	v_lshlrev_b32_e32 v34, 16, v48
	v_and_b32_e32 v35, 0xffff0000, v48
	v_lshlrev_b32_e32 v36, 16, v52
	v_and_b32_e32 v37, 0xffff0000, v52
	v_lshlrev_b32_e32 v74, 16, v51
	v_and_b32_e32 v75, 0xffff0000, v51
	v_lshlrev_b32_e32 v88, 16, v50
	v_and_b32_e32 v89, 0xffff0000, v50
	flat_load_dwordx4 v[44:47], v[32:33] offset:16
	flat_load_dwordx4 v[48:51], v[32:33]
	flat_load_dwordx4 v[52:55], v[32:33] offset:80
	flat_load_dwordx4 v[56:59], v[32:33] offset:64
	v_add_f32_e32 v38, v68, v38
	v_pk_mul_f32 v[64:65], v[34:35], v[34:35]
	v_add_f32_e32 v38, v69, v38
	v_add_f32_e32 v38, v64, v38
	v_pk_mul_f32 v[60:61], v[20:21], v[20:21]
	v_add_f32_e32 v38, v65, v38
	v_add_f32_e32 v38, v60, v38
	v_pk_mul_f32 v[80:81], v[88:89], v[88:89]
	v_add_f32_e32 v38, v61, v38
	v_add_f32_e32 v38, v80, v38
	v_pk_mul_f32 v[70:71], v[74:75], v[74:75]
	v_add_f32_e32 v38, v81, v38
	v_add_f32_e32 v38, v70, v38
	v_pk_mul_f32 v[66:67], v[36:37], v[36:37]
	v_add_f32_e32 v38, v71, v38
	v_add_f32_e32 v38, v66, v38
	v_pk_mul_f32 v[62:63], v[24:25], v[24:25]
	v_add_f32_e32 v38, v67, v38
	v_add_f32_e32 v38, v62, v38
	v_add_f32_e32 v42, v63, v38
	flat_load_dwordx4 v[38:41], v[32:33] offset:144
	flat_load_dwordx4 v[60:63], v[32:33] offset:128
	flat_load_dwordx4 v[64:67], v[32:33] offset:208
	flat_load_dwordx4 v[68:71], v[32:33] offset:192
	ds_bpermute_b32 v43, v218, v42
	v_mul_f32_e32 v78, v111, v110
	v_sin_f32_e32 v2, v2
	v_mul_f32_e32 v7, 0.15915494, v5
	v_cos_f32_e32 v5, v7
	s_waitcnt lgkmcnt(0)
	v_add_f32_e32 v32, v42, v43
	v_fmamk_f32 v32, v32, 0x3c800000, v210
	v_mul_f32_e32 v33, 0x4f800000, v32
	v_cmp_gt_f32_e32 vcc, s64, v32
	v_sin_f32_e32 v7, v7
	v_sin_f32_e32 v42, v112
	v_cndmask_b32_e32 v33, v32, v33, vcc
	v_sqrt_f32_e32 v43, v33
	v_cos_f32_e32 v32, v112
	s_mov_b32 s76, 2
	s_mov_b32 s33, 1
	v_add_u32_e32 v79, -1, v43
	v_fma_f32 v80, -v79, v43, v33
	v_cmp_ge_f32_e64 s[8:9], 0, v80
	v_add_u32_e32 v80, 1, v43
	s_mov_b32 s77, 0
	v_cndmask_b32_e64 v79, v43, v79, s[8:9]
	v_fma_f32 v43, -v80, v43, v33
	v_cmp_lt_f32_e64 s[8:9], 0, v43
	v_readlane_b32 s49, v242, 18
	v_readlane_b32 s52, v242, 21
	v_cndmask_b32_e64 v43, v79, v80, s[8:9]
	v_mul_f32_e32 v79, 0x37800000, v43
	v_cndmask_b32_e32 v43, v43, v79, vcc
	v_cmp_class_f32_e32 vcc, v33, v211
	v_readlane_b32 s53, v242, 22
	v_readlane_b32 s54, v242, 23
	v_cndmask_b32_e32 v79, v43, v33, vcc
	v_div_scale_f32 v80, s[8:9], v79, v79, s65
	v_rcp_f32_e32 v81, v80
	v_mul_f32_e32 v43, 0.15915494, v78
	v_cos_f32_e32 v33, v43
	v_sin_f32_e32 v43, v43
	v_fma_f32 v78, -v80, v81, 1.0
	v_fmac_f32_e32 v81, v78, v81
	v_div_scale_f32 v78, vcc, s65, v79, s65
	v_mul_f32_e32 v84, v78, v81
	v_fma_f32 v85, -v80, v84, v78
	v_fmac_f32_e32 v84, v85, v81
	v_fma_f32 v78, -v80, v84, v78
	v_div_fmas_f32 v78, v78, v81, v84
	v_div_fixup_f32 v78, v78, v79, s65
	v_pk_mul_f32 v[80:81], v[78:79], v[106:107] op_sel_hi:[0,1]
	v_readlane_b32 s55, v242, 24
	v_readlane_b32 s56, v242, 25
	v_readlane_b32 s57, v242, 26
	v_readlane_b32 s58, v242, 27
	v_readlane_b32 s59, v242, 28
	v_readlane_b32 s60, v242, 29
	s_waitcnt vmcnt(0)
	v_pk_mul_f32 v[48:49], v[48:49], v[80:81]
	v_pk_mul_f32 v[80:81], v[78:79], v[108:109] op_sel_hi:[0,1]
	v_pk_mul_f32 v[56:57], v[56:57], v[80:81]
	v_readlane_b32 s61, v242, 30
	v_pk_mul_f32 v[80:81], v[0:1], v[56:57]
	v_readlane_b32 s62, v242, 31
	v_pk_fma_f32 v[84:85], v[2:3], v[48:49], v[80:81]
	v_pk_mul_f32 v[2:3], v[2:3], v[56:57]
	v_cvt_pk_bf16_f32 v84, v84, v85
	v_pk_fma_f32 v[0:1], v[0:1], v[48:49], v[2:3] neg_lo:[0,0,1] neg_hi:[0,0,1]
	v_pk_mul_f32 v[48:49], v[78:79], v[102:103] op_sel_hi:[0,1]
	v_pk_mul_f32 v[2:3], v[78:79], v[98:99] op_sel_hi:[0,1]
	v_pk_mul_f32 v[48:49], v[58:59], v[48:49]
	v_pk_mul_f32 v[2:3], v[50:51], v[2:3]
	v_pk_mul_f32 v[50:51], v[8:9], v[48:49]
	v_cvt_pk_bf16_f32 v80, v0, v1
	v_pk_fma_f32 v[50:51], v[14:15], v[2:3], v[50:51]
	v_pk_mul_f32 v[14:15], v[14:15], v[48:49]
	v_pk_mul_f32 v[0:1], v[78:79], v[76:77] op_sel_hi:[0,1]
	v_pk_fma_f32 v[2:3], v[8:9], v[2:3], v[14:15] neg_lo:[0,0,1] neg_hi:[0,0,1]
	v_pk_mul_f32 v[14:15], v[78:79], v[94:95] op_sel_hi:[0,1]
	v_pk_mul_f32 v[8:9], v[78:79], v[92:93] op_sel_hi:[0,1]
	v_pk_mul_f32 v[14:15], v[52:53], v[14:15]
	v_pk_mul_f32 v[8:9], v[44:45], v[8:9]
	v_pk_mul_f32 v[44:45], v[22:23], v[14:15]
	v_pk_mul_f32 v[14:15], v[26:27], v[14:15]
	v_pk_fma_f32 v[44:45], v[26:27], v[8:9], v[44:45]
	v_pk_fma_f32 v[8:9], v[22:23], v[8:9], v[14:15] neg_lo:[0,0,1] neg_hi:[0,0,1]
	v_pk_mul_f32 v[22:23], v[78:79], v[86:87] op_sel_hi:[0,1]
	v_pk_mul_f32 v[14:15], v[78:79], v[82:83] op_sel_hi:[0,1]
	v_pk_mul_f32 v[22:23], v[54:55], v[22:23]
	v_pk_mul_f32 v[14:15], v[46:47], v[14:15]
	v_pk_mul_f32 v[26:27], v[28:29], v[22:23]
	v_pk_mul_f32 v[22:23], v[30:31], v[22:23]
	v_cvt_pk_bf16_f32 v81, v2, v3
	v_pk_mul_f32 v[2:3], v[78:79], v[88:89] op_sel_hi:[0,1]
	v_pk_fma_f32 v[26:27], v[30:31], v[14:15], v[26:27]
	v_pk_fma_f32 v[14:15], v[28:29], v[14:15], v[22:23] neg_lo:[0,0,1] neg_hi:[0,0,1]
	v_pk_mul_f32 v[2:3], v[68:69], v[2:3]
	v_cvt_pk_bf16_f32 v82, v8, v9
	v_cvt_pk_bf16_f32 v83, v14, v15
	v_pk_mul_f32 v[0:1], v[60:61], v[0:1]
	v_pk_mul_f32 v[8:9], v[16:17], v[2:3]
	v_pk_mul_f32 v[2:3], v[18:19], v[2:3]
	v_pk_mul_f32 v[14:15], v[78:79], v[74:75] op_sel_hi:[0,1]
	v_pk_fma_f32 v[8:9], v[18:19], v[0:1], v[8:9]
	v_pk_fma_f32 v[0:1], v[16:17], v[0:1], v[2:3] neg_lo:[0,0,1] neg_hi:[0,0,1]
	v_pk_mul_f32 v[2:3], v[78:79], v[72:73] op_sel_hi:[0,1]
	v_pk_mul_f32 v[14:15], v[70:71], v[14:15]
	v_pk_mul_f32 v[2:3], v[62:63], v[2:3]
	v_pk_mul_f32 v[16:17], v[10:11], v[14:15]
	v_cvt_pk_bf16_f32 v85, v50, v51
	v_pk_fma_f32 v[16:17], v[12:13], v[2:3], v[16:17]
	v_pk_mul_f32 v[12:13], v[12:13], v[14:15]
	v_cvt_pk_bf16_f32 v86, v44, v45
	v_pk_fma_f32 v[2:3], v[10:11], v[2:3], v[12:13] neg_lo:[0,0,1] neg_hi:[0,0,1]
	v_pk_mul_f32 v[12:13], v[78:79], v[36:37] op_sel_hi:[0,1]
	v_pk_mul_f32 v[10:11], v[78:79], v[34:35] op_sel_hi:[0,1]
	v_pk_mul_f32 v[12:13], v[64:65], v[12:13]
	v_pk_mul_f32 v[10:11], v[38:39], v[10:11]
	v_pk_mul_f32 v[14:15], v[4:5], v[12:13]
	v_cvt_pk_bf16_f32 v87, v26, v27
	v_pk_fma_f32 v[14:15], v[6:7], v[10:11], v[14:15]
	v_pk_mul_f32 v[6:7], v[6:7], v[12:13]
	v_cvt_pk_bf16_f32 v92, v0, v1
	v_pk_fma_f32 v[4:5], v[4:5], v[10:11], v[6:7] neg_lo:[0,0,1] neg_hi:[0,0,1]
	v_pk_mul_f32 v[10:11], v[78:79], v[24:25] op_sel_hi:[0,1]
	v_pk_mul_f32 v[6:7], v[78:79], v[20:21] op_sel_hi:[0,1]
	v_pk_mul_f32 v[10:11], v[66:67], v[10:11]
	v_pk_mul_f32 v[6:7], v[40:41], v[6:7]
	v_pk_mul_f32 v[12:13], v[32:33], v[10:11]
	v_pk_mul_f32 v[10:11], v[42:43], v[10:11]
	v_pk_fma_f32 v[12:13], v[42:43], v[6:7], v[12:13]
	v_pk_fma_f32 v[6:7], v[32:33], v[6:7], v[10:11] neg_lo:[0,0,1] neg_hi:[0,0,1]
	v_cvt_pk_bf16_f32 v93, v2, v3
	v_cvt_pk_bf16_f32 v94, v4, v5
	v_cvt_pk_bf16_f32 v95, v6, v7
	v_cvt_pk_bf16_f32 v88, v8, v9
	v_cvt_pk_bf16_f32 v89, v16, v17
	v_cvt_pk_bf16_f32 v90, v14, v15
	v_cvt_pk_bf16_f32 v91, v12, v13
	v_readlane_b32 s63, v242, 32
	v_mov_b32_e32 v189, v173
	v_lshl_add_u64 v[44:45], s[42:43], 0, v[188:189]
	s_movk_i32 s8, 0x2000
	v_lshl_add_u64 v[0:1], s[44:45], 0, v[172:173]
	v_mov_b32_e32 v187, v173
	v_add_co_u32_e32 v24, vcc, s8, v44
	v_lshl_add_u64 v[196:197], v[0:1], 0, v[186:187]
	v_mov_b32_e32 v0, v173
	v_mov_b32_e32 v1, v173
	v_mov_b32_e32 v2, v173
	v_mov_b32_e32 v3, v173
	v_mov_b32_e32 v4, v173
	v_mov_b32_e32 v5, v173
	v_mov_b32_e32 v6, v173
	v_mov_b32_e32 v7, v173
	v_mov_b32_e32 v8, v173
	v_mov_b32_e32 v9, v173
	v_mov_b32_e32 v10, v173
	v_mov_b32_e32 v11, v173
	v_mov_b32_e32 v12, v173
	v_mov_b32_e32 v13, v173
	v_mov_b32_e32 v14, v173
	v_mov_b32_e32 v15, v173
	v_addc_co_u32_e32 v25, vcc, 0, v45, vcc
	global_load_dwordx4 v[16:19], v188, s[42:43]
	global_load_dwordx4 v[20:23], v[196:197], off
	s_nop 0
	global_load_dwordx4 v[24:27], v[24:25], off
	global_load_dwordx4 v[28:31], v[196:197], off offset:128
	s_movk_i32 s8, 0x4000
	s_waitcnt vmcnt(3)
	ds_write_b128 v177, v[16:19]
	s_waitcnt vmcnt(2)
	ds_write2_b64 v215, v[20:21], v[22:23] offset1:2
	s_waitcnt vmcnt(1)
	ds_write_b128 v177, v[24:27] offset:9216
	s_waitcnt vmcnt(0)
	ds_write2_b64 v216, v[28:29], v[30:31] offset0:128 offset1:130
	s_waitcnt lgkmcnt(0)
	s_barrier
	ds_read_b128 v[32:35], v199
	ds_read_b128 v[36:39], v199 offset:32
	s_waitcnt lgkmcnt(1)
	v_mfma_f32_32x32x16_bf16 v[16:31], v[32:35], v[80:83], v[0:15]
	ds_read_b128 v[32:35], v199 offset:4608
	ds_read_b128 v[40:43], v199 offset:4640
	s_waitcnt lgkmcnt(1)
	v_mfma_f32_32x32x16_bf16 v[0:15], v[32:35], v[80:83], v[0:15]
	v_mfma_f32_32x32x16_bf16 v[16:31], v[36:39], v[84:87], v[16:31]
	ds_read_b128 v[32:35], v199 offset:64
	ds_read_b128 v[36:39], v199 offset:96
	s_waitcnt lgkmcnt(2)
	v_mfma_f32_32x32x16_bf16 v[0:15], v[40:43], v[84:87], v[0:15]
	s_waitcnt lgkmcnt(1)
	v_mfma_f32_32x32x16_bf16 v[16:31], v[32:35], v[92:95], v[16:31]
	ds_read_b128 v[32:35], v199 offset:4672
	ds_read_b128 v[40:43], v199 offset:4704
	s_waitcnt lgkmcnt(1)
	v_mfma_f32_32x32x16_bf16 v[0:15], v[32:35], v[92:95], v[0:15]
	v_add_co_u32_e32 v32, vcc, s8, v44
	s_nop 1
	v_addc_co_u32_e32 v33, vcc, 0, v45, vcc
	global_load_dwordx4 v[52:55], v[32:33], off
	global_load_dwordx4 v[48:51], v[196:197], off offset:256
	v_mfma_f32_32x32x16_bf16 v[16:31], v[36:39], v[88:91], v[16:31]
	s_waitcnt lgkmcnt(0)
	v_mfma_f32_32x32x16_bf16 v[0:15], v[40:43], v[88:91], v[0:15]
	s_setprio 0
	ds_read_b128 v[96:99], v199 offset:18432
	ds_read_b128 v[68:71], v199 offset:18464
	ds_read_b128 v[100:103], v199 offset:23040
	ds_read_b128 v[72:75], v199 offset:23072
	ds_read_b128 v[64:67], v199 offset:18496
	ds_read_b128 v[60:63], v199 offset:18528
	ds_read_b128 v[76:79], v199 offset:23104
	ds_read_b128 v[56:59], v199 offset:23136
	s_nop 3
	v_mov_b32_e32 v33, s99
	s_cmp_eq_u32 s98, 0
	s_cbranch_scc1 .Lstg_x_1
	s_waitcnt lgkmcnt(0)
	s_barrier
.Lstg_x_1:
	v_sub_f32_e32 v0, v0, v33
	v_sub_f32_e32 v32, v7, v33
	v_sub_f32_e32 v7, v16, v33
	v_sub_f32_e32 v1, v1, v33
	v_sub_f32_e32 v34, v8, v33
	v_sub_f32_e32 v37, v11, v33
	v_sub_f32_e32 v8, v17, v33
	v_sub_f32_e32 v11, v20, v33
	v_sub_f32_e32 v20, v28, v33
	v_exp_f32_e32 v28, v7
	v_exp_f32_e32 v108, v0
	v_sub_f32_e32 v39, v13, v33
	v_sub_f32_e32 v40, v14, v33
	v_sub_f32_e32 v13, v22, v33
	v_sub_f32_e32 v14, v23, v33
	v_sub_f32_e32 v22, v29, v33
	v_sub_f32_e32 v23, v30, v33
	v_exp_f32_e32 v29, v8
	v_exp_f32_e32 v30, v1
	v_sub_f32_e32 v2, v2, v33
	v_sub_f32_e32 v35, v9, v33
	v_sub_f32_e32 v9, v18, v33
	v_sub_f32_e32 v3, v3, v33
	v_sub_f32_e32 v36, v10, v33
	v_sub_f32_e32 v41, v15, v33
	v_sub_f32_e32 v10, v19, v33
	v_sub_f32_e32 v15, v24, v33
	v_sub_f32_e32 v24, v31, v33
	v_add_f32_e32 v0, v28, v108
	v_exp_f32_e32 v31, v9
	v_exp_f32_e32 v109, v2
	v_sub_f32_e32 v4, v4, v33
	v_sub_f32_e32 v5, v5, v33
	v_sub_f32_e32 v38, v12, v33
	v_sub_f32_e32 v12, v21, v33
	v_add_f32_e32 v0, 0, v0
	v_add_f32_e32 v1, v29, v30
	v_exp_f32_e32 v104, v10
	v_exp_f32_e32 v110, v3
	v_add_f32_e32 v7, v1, v0
	v_exp_f32_e32 v1, v11
	v_exp_f32_e32 v3, v4
	v_exp_f32_e32 v0, v12
	v_exp_f32_e32 v2, v5
	v_add_f32_e32 v8, v31, v109
	v_add_f32_e32 v4, v8, v7
	v_add_f32_e32 v5, v104, v110
	v_sub_f32_e32 v6, v6, v33
	v_add_f32_e32 v7, v5, v4
	v_pk_add_f32 v[4:5], v[0:1], v[2:3]
	v_exp_f32_e32 v9, v6
	v_add_f32_e32 v5, v5, v7
	v_exp_f32_e32 v7, v13
	v_exp_f32_e32 v6, v14
	v_exp_f32_e32 v8, v32
	v_sub_f32_e32 v16, v25, v33
	v_pk_mov_b32 v[10:11], v[0:1], v[0:1] op_sel:[1,0]
	v_pk_mov_b32 v[12:13], v[2:3], v[2:3] op_sel:[1,0]
	v_add_f32_e32 v2, v4, v5
	v_pk_add_f32 v[0:1], v[6:7], v[8:9]
	v_exp_f32_e32 v3, v15
	v_add_f32_e32 v1, v1, v2
	v_exp_f32_e32 v5, v34
	v_exp_f32_e32 v2, v16
	v_exp_f32_e32 v4, v35
	v_sub_f32_e32 v17, v26, v33
	v_sub_f32_e32 v18, v27, v33
	v_add_f32_e32 v14, v0, v1
	v_pk_add_f32 v[0:1], v[2:3], v[4:5]
	v_exp_f32_e32 v15, v17
	v_add_f32_e32 v1, v1, v14
	v_exp_f32_e32 v17, v36
	v_exp_f32_e32 v14, v18
	v_exp_f32_e32 v16, v37
	v_pk_mov_b32 v[18:19], v[2:3], v[2:3] op_sel:[1,0]
	v_add_f32_e32 v2, v0, v1
	v_exp_f32_e32 v3, v20
	v_pk_add_f32 v[0:1], v[14:15], v[16:17]
	v_exp_f32_e32 v21, v38
	v_add_f32_e32 v1, v1, v2
	v_exp_f32_e32 v2, v22
	v_exp_f32_e32 v20, v39
	v_add_f32_e32 v22, v0, v1
	v_exp_f32_e32 v23, v23
	v_exp_f32_e32 v25, v40
	v_pk_add_f32 v[0:1], v[2:3], v[20:21]
	v_pk_mov_b32 v[26:27], v[2:3], v[2:3] op_sel:[1,0]
	v_add_f32_e32 v1, v1, v22
	v_exp_f32_e32 v22, v24
	v_exp_f32_e32 v24, v41
	v_add_f32_e32 v2, v0, v1
	v_pk_mov_b32 v[6:7], v[6:7], v[6:7] op_sel:[1,0]
	v_pk_mov_b32 v[8:9], v[8:9], v[8:9] op_sel:[1,0]
	v_pk_add_f32 v[0:1], v[22:23], v[24:25]
	v_pk_mov_b32 v[4:5], v[4:5], v[4:5] op_sel:[1,0]
	v_add_f32_e32 v1, v1, v2
	v_add_f32_e32 v32, v0, v1
	v_pk_add_f32 v[194:195], v[32:33], 0 op_sel_hi:[1,0]
	v_pk_mov_b32 v[14:15], v[14:15], v[14:15] op_sel:[1,0]
	v_xor_b32_e32 v32, 0x80000000, v195
	v_pk_mov_b32 v[16:17], v[16:17], v[16:17] op_sel:[1,0]
	v_pk_mov_b32 v[20:21], v[20:21], v[20:21] op_sel:[1,0]
	v_pk_mov_b32 v[22:23], v[22:23], v[22:23] op_sel:[1,0]
	v_pk_mov_b32 v[24:25], v[24:25], v[24:25] op_sel:[1,0]
	v_mov_b32_e32 v33, v32
	v_mov_b32_e32 v34, v32
	v_mov_b32_e32 v35, v32
	v_mov_b32_e32 v36, v32
	v_mov_b32_e32 v37, v32
	v_mov_b32_e32 v38, v32
	v_mov_b32_e32 v39, v32
	v_mov_b32_e32 v40, v32
	v_mov_b32_e32 v41, v32
	v_mov_b32_e32 v42, v32
	v_mov_b32_e32 v43, v32
	v_mov_b32_e32 v44, v32
	v_mov_b32_e32 v45, v32
	v_mov_b32_e32 v46, v32
	v_mov_b32_e32 v47, v32
	v_cvt_pk_bf16_f32 v0, v28, v29
	v_cvt_pk_bf16_f32 v1, v31, v104
	v_cvt_pk_bf16_f32 v2, v10, v11
	v_cvt_pk_bf16_f32 v3, v6, v7
	v_cvt_pk_bf16_f32 v104, v18, v19
	v_cvt_pk_bf16_f32 v105, v14, v15
	v_cvt_pk_bf16_f32 v106, v26, v27
	v_cvt_pk_bf16_f32 v107, v22, v23
	v_cvt_pk_bf16_f32 v108, v108, v30
	v_cvt_pk_bf16_f32 v109, v109, v110
	v_cvt_pk_bf16_f32 v110, v12, v13
	v_cvt_pk_bf16_f32 v111, v8, v9
	v_cvt_pk_bf16_f32 v112, v4, v5
	v_cvt_pk_bf16_f32 v113, v16, v17
	v_cvt_pk_bf16_f32 v114, v20, v21
	v_cvt_pk_bf16_f32 v115, v24, v25
	s_setprio 1
	s_cmp_lg_u32 s98, 0
	s_cbranch_scc1 .Lstg_y_2
	s_waitcnt lgkmcnt(0)
	s_barrier

.LBB0_336:
	global_load_dwordx4 v[104:107], v[190:191], off
	global_load_dwordx4 v[96:99], v[192:193], off
	s_waitcnt lgkmcnt(9)
	v_mfma_f32_32x32x16_bf16 v[64:79], v[160:163], v[80:83], v[32:47]
	s_mov_b32 s8, s33
	s_waitcnt lgkmcnt(7)
	v_mfma_f32_32x32x16_bf16 v[48:63], v[164:167], v[80:83], v[32:47]
	v_mfma_f32_32x32x16_bf16 v[64:79], v[156:159], v[84:87], v[64:79]
	s_waitcnt lgkmcnt(6)
	v_mfma_f32_32x32x16_bf16 v[48:63], v[152:155], v[84:87], v[48:63]
	s_waitcnt lgkmcnt(5)
	v_mfma_f32_32x32x16_bf16 v[64:79], v[144:147], v[92:95], v[64:79]
	s_waitcnt lgkmcnt(3)
	v_mfma_f32_32x32x16_bf16 v[48:63], v[148:151], v[92:95], v[48:63]
	v_mfma_f32_32x32x16_bf16 v[64:79], v[140:143], v[88:91], v[64:79]
	s_waitcnt lgkmcnt(2)
	v_mfma_f32_32x32x16_bf16 v[48:63], v[136:139], v[88:91], v[48:63]
	s_setprio 0
	s_and_b32 s33, 1, s76
	s_cselect_b32 s9, 0, 0x2400
	v_add_u32_e32 v100, s9, v199
	ds_read_b128 v[128:131], v100 offset:18432
	ds_read_b128 v[116:119], v100 offset:18464
	ds_read_b128 v[132:135], v100 offset:23040
	ds_read_b128 v[120:123], v100 offset:23072
	ds_read_b128 v[112:115], v100 offset:18496
	ds_read_b128 v[108:111], v100 offset:18528
	ds_read_b128 v[124:127], v100 offset:23104
	ds_read_b128 v[100:103], v100 offset:23136
.LBB0_338:
	v_exp_f32_e32 v136, v64
	v_exp_f32_e32 v137, v48
	v_exp_f32_e32 v138, v65
	v_exp_f32_e32 v139, v49
	v_exp_f32_e32 v140, v66
	v_exp_f32_e32 v141, v50
	v_exp_f32_e32 v142, v67
	v_exp_f32_e32 v143, v51
	s_cmp_eq_u32 s98, 0
	s_cbranch_scc1 .Lstg_x_3
	s_waitcnt lgkmcnt(0)
	s_barrier
.Lstg_x_3:
	v_add_f32_e32 v48, v137, v136
	v_add_f32_e32 v48, 0, v48
	v_add_f32_e32 v49, v139, v138
	v_add_f32_e32 v48, v49, v48
	v_add_f32_e32 v49, v141, v140
	v_exp_f32_e32 v144, v68
	v_exp_f32_e32 v145, v52
	v_add_f32_e32 v48, v49, v48
	v_add_f32_e32 v49, v143, v142
	v_exp_f32_e32 v146, v69
	v_exp_f32_e32 v147, v53
	v_add_f32_e32 v52, v49, v48
	v_exp_f32_e32 v49, v70
	v_exp_f32_e32 v51, v54
	v_exp_f32_e32 v48, v71
	v_exp_f32_e32 v50, v55
	v_add_f32_e32 v64, v145, v144
	v_add_f32_e32 v52, v64, v52
	v_add_f32_e32 v53, v147, v146
	v_add_f32_e32 v54, v53, v52
	v_pk_add_f32 v[52:53], v[50:51], v[48:49]
	v_exp_f32_e32 v55, v72
	v_add_f32_e32 v53, v53, v54
	v_exp_f32_e32 v65, v56
	v_exp_f32_e32 v54, v73
	v_exp_f32_e32 v64, v57
	v_pk_mov_b32 v[56:57], v[48:49], v[48:49] op_sel:[1,0]
	v_pk_mov_b32 v[66:67], v[50:51], v[50:51] op_sel:[1,0]
	v_add_f32_e32 v50, v52, v53
	v_pk_add_f32 v[48:49], v[64:65], v[54:55]
	v_exp_f32_e32 v51, v74
	v_add_f32_e32 v49, v49, v50
	v_exp_f32_e32 v53, v58
	v_exp_f32_e32 v50, v75
	v_exp_f32_e32 v52, v59
	v_add_f32_e32 v58, v48, v49
	v_exp_f32_e32 v59, v76
	v_exp_f32_e32 v69, v60
	v_pk_add_f32 v[48:49], v[52:53], v[50:51]
	v_exp_f32_e32 v68, v61
	v_add_f32_e32 v49, v49, v58
	v_exp_f32_e32 v58, v77
	v_pk_mov_b32 v[60:61], v[50:51], v[50:51] op_sel:[1,0]
	v_add_f32_e32 v50, v48, v49
	v_pk_mov_b32 v[70:71], v[52:53], v[52:53] op_sel:[1,0]
	v_pk_add_f32 v[48:49], v[68:69], v[58:59]
	v_exp_f32_e32 v51, v78
	v_add_f32_e32 v49, v49, v50
	v_exp_f32_e32 v53, v62
	v_exp_f32_e32 v50, v79
	v_exp_f32_e32 v52, v63
	v_pk_mov_b32 v[62:63], v[68:69], v[68:69] op_sel:[1,0]
	v_add_f32_e32 v68, v48, v49
	v_pk_mov_b32 v[54:55], v[54:55], v[54:55] op_sel:[1,0]
	v_pk_add_f32 v[48:49], v[52:53], v[50:51]
	v_pk_mov_b32 v[64:65], v[64:65], v[64:65] op_sel:[1,0]
	v_add_f32_e32 v49, v49, v68
	v_add_f32_e32 v48, v48, v49
	v_pk_mov_b32 v[58:59], v[58:59], v[58:59] op_sel:[1,0]
	v_pk_mov_b32 v[68:69], v[50:51], v[50:51] op_sel:[1,0]
	v_pk_mov_b32 v[72:73], v[52:53], v[52:53] op_sel:[1,0]
	v_add_f32_e32 v194, v194, v48
	v_cvt_pk_bf16_f32 v48, v136, v138
	v_cvt_pk_bf16_f32 v49, v140, v142
	v_cvt_pk_bf16_f32 v50, v144, v146
	v_cvt_pk_bf16_f32 v51, v56, v57
	v_cvt_pk_bf16_f32 v52, v54, v55
	v_cvt_pk_bf16_f32 v53, v60, v61
	v_cvt_pk_bf16_f32 v54, v58, v59
	v_cvt_pk_bf16_f32 v55, v68, v69
	v_cvt_pk_bf16_f32 v56, v137, v139
	v_cvt_pk_bf16_f32 v57, v141, v143
	v_cvt_pk_bf16_f32 v58, v145, v147
	v_cvt_pk_bf16_f32 v59, v66, v67
	v_cvt_pk_bf16_f32 v60, v64, v65
	v_cvt_pk_bf16_f32 v61, v70, v71
	v_cvt_pk_bf16_f32 v62, v62, v63
	v_cvt_pk_bf16_f32 v63, v72, v73
	s_setprio 1
	s_cmp_lg_u32 s98, 0
	s_cbranch_scc1 .Lstg_y_4
	s_waitcnt lgkmcnt(0)
	s_barrier

.LBB0_340:
	s_waitcnt lgkmcnt(9)
	v_mfma_f32_32x32x16_bf16 v[64:79], v[160:163], v[80:83], v[32:47]
	s_waitcnt lgkmcnt(7)
	v_mfma_f32_32x32x16_bf16 v[48:63], v[164:167], v[80:83], v[32:47]
	v_mfma_f32_32x32x16_bf16 v[64:79], v[156:159], v[84:87], v[64:79]
	s_waitcnt lgkmcnt(6)
	v_mfma_f32_32x32x16_bf16 v[48:63], v[152:155], v[84:87], v[48:63]
	s_waitcnt lgkmcnt(5)
	v_mfma_f32_32x32x16_bf16 v[64:79], v[144:147], v[92:95], v[64:79]
	s_waitcnt lgkmcnt(3)
	v_mfma_f32_32x32x16_bf16 v[48:63], v[148:151], v[92:95], v[48:63]
	v_mfma_f32_32x32x16_bf16 v[64:79], v[140:143], v[88:91], v[64:79]
	s_waitcnt lgkmcnt(2)
	v_mfma_f32_32x32x16_bf16 v[48:63], v[136:139], v[88:91], v[48:63]
	s_setprio 0
	ds_read_b128 v[124:127], v199 offset:18432
	ds_read_b128 v[112:115], v199 offset:18464
	ds_read_b128 v[128:131], v199 offset:23040
	ds_read_b128 v[116:119], v199 offset:23072
	ds_read_b128 v[108:111], v199 offset:18496
	ds_read_b128 v[100:103], v199 offset:18528
	ds_read_b128 v[120:123], v199 offset:23104
	ds_read_b128 v[104:107], v199 offset:23136
	s_nop 1
	s_nop 0
	s_cmp_eq_u32 s98, 0
	s_cbranch_scc1 .Lstg_x_5
	s_waitcnt lgkmcnt(0)
	s_barrier
.Lstg_x_5:
.LBB0_342:
	v_exp_f32_e32 v133, v64
	v_exp_f32_e32 v134, v48
	v_exp_f32_e32 v135, v65
	v_exp_f32_e32 v136, v49
	v_exp_f32_e32 v137, v66
	v_add_f32_e32 v48, v134, v133
	v_exp_f32_e32 v138, v50
	v_add_f32_e32 v48, 0, v48
	v_add_f32_e32 v49, v136, v135
	v_exp_f32_e32 v139, v67
	v_exp_f32_e32 v140, v51
	v_add_f32_e32 v64, v49, v48
	v_exp_f32_e32 v49, v68
	v_exp_f32_e32 v51, v52
	v_exp_f32_e32 v48, v69
	v_exp_f32_e32 v50, v53
	v_add_f32_e32 v65, v138, v137
	v_add_f32_e32 v52, v65, v64
	v_add_f32_e32 v53, v140, v139
	v_add_f32_e32 v64, v53, v52
	v_pk_add_f32 v[52:53], v[50:51], v[48:49]
	v_exp_f32_e32 v65, v70
	v_add_f32_e32 v53, v53, v64
	v_exp_f32_e32 v67, v54
	v_exp_f32_e32 v64, v71
	v_exp_f32_e32 v66, v55
	v_pk_mov_b32 v[54:55], v[48:49], v[48:49] op_sel:[1,0]
	v_pk_mov_b32 v[68:69], v[50:51], v[50:51] op_sel:[1,0]
	v_add_f32_e32 v50, v52, v53
	v_pk_add_f32 v[48:49], v[66:67], v[64:65]
	v_exp_f32_e32 v51, v72
	v_add_f32_e32 v49, v49, v50
	v_exp_f32_e32 v53, v56
	v_exp_f32_e32 v50, v73
	v_exp_f32_e32 v52, v57
	v_pk_mov_b32 v[56:57], v[64:65], v[64:65] op_sel:[1,0]
	v_pk_mov_b32 v[64:65], v[66:67], v[66:67] op_sel:[1,0]
	v_add_f32_e32 v66, v48, v49
	v_pk_add_f32 v[48:49], v[52:53], v[50:51]
	v_exp_f32_e32 v67, v74
	v_add_f32_e32 v49, v49, v66
	v_exp_f32_e32 v71, v58
	v_exp_f32_e32 v66, v75
	v_exp_f32_e32 v70, v59
	v_pk_mov_b32 v[58:59], v[50:51], v[50:51] op_sel:[1,0]
	v_add_f32_e32 v50, v48, v49
	v_pk_mov_b32 v[72:73], v[52:53], v[52:53] op_sel:[1,0]
	v_pk_add_f32 v[48:49], v[70:71], v[66:67]
	v_exp_f32_e32 v51, v76
	v_add_f32_e32 v49, v49, v50
	v_exp_f32_e32 v53, v60
	v_exp_f32_e32 v50, v77
	v_exp_f32_e32 v52, v61
	v_pk_mov_b32 v[60:61], v[66:67], v[66:67] op_sel:[1,0]
	v_pk_mov_b32 v[66:67], v[70:71], v[70:71] op_sel:[1,0]
	v_add_f32_e32 v70, v48, v49
	v_pk_add_f32 v[48:49], v[52:53], v[50:51]
	v_exp_f32_e32 v71, v78
	v_add_f32_e32 v49, v49, v70
	v_exp_f32_e32 v75, v62
	v_exp_f32_e32 v70, v79
	v_exp_f32_e32 v74, v63
	v_pk_mov_b32 v[62:63], v[50:51], v[50:51] op_sel:[1,0]
	v_add_f32_e32 v50, v48, v49
	v_pk_mov_b32 v[76:77], v[52:53], v[52:53] op_sel:[1,0]
	v_pk_add_f32 v[48:49], v[74:75], v[70:71]
	v_pk_mov_b32 v[70:71], v[70:71], v[70:71] op_sel:[1,0]
	v_add_f32_e32 v49, v49, v50
	v_pk_mov_b32 v[74:75], v[74:75], v[74:75] op_sel:[1,0]
	v_add_f32_e32 v48, v48, v49
	v_add_f32_e32 v132, v194, v48
	v_cvt_pk_bf16_f32 v48, v133, v135
	v_cvt_pk_bf16_f32 v49, v137, v139
	v_cvt_pk_bf16_f32 v50, v54, v55
	v_cvt_pk_bf16_f32 v51, v56, v57
	v_cvt_pk_bf16_f32 v52, v58, v59
	v_cvt_pk_bf16_f32 v53, v60, v61
	v_cvt_pk_bf16_f32 v54, v62, v63
	v_cvt_pk_bf16_f32 v55, v70, v71
	v_cvt_pk_bf16_f32 v56, v134, v136
	v_cvt_pk_bf16_f32 v57, v138, v140
	v_cvt_pk_bf16_f32 v58, v68, v69
	v_cvt_pk_bf16_f32 v59, v64, v65
	v_cvt_pk_bf16_f32 v60, v72, v73
	v_cvt_pk_bf16_f32 v61, v66, v67
	v_cvt_pk_bf16_f32 v62, v76, v77
	v_cvt_pk_bf16_f32 v63, v74, v75
	s_setprio 1
	s_cmp_lg_u32 s98, 0
	s_cbranch_scc1 .Lstg_y_6
	s_waitcnt lgkmcnt(0)
	s_barrier
.Lstg_y_6:
	v_add_u32_e32 v133, s9, v199
	ds_read_b128 v[64:67], v133
	ds_read_b128 v[68:71], v133 offset:32
	ds_read_b128 v[72:75], v133 offset:4608
	ds_read_b128 v[76:79], v133 offset:4640
	ds_read_b128 v[134:137], v133 offset:64
	ds_read_b128 v[138:141], v133 offset:96
	ds_read_b128 v[142:145], v133 offset:4672
	ds_read_b128 v[146:149], v133 offset:4704
	s_waitcnt lgkmcnt(14)
	v_mfma_f32_32x32x16_bf16 v[16:31], v[124:127], v[48:51], v[16:31]
	s_waitcnt lgkmcnt(14)
	v_mfma_f32_32x32x16_bf16 v[0:15], v[128:131], v[48:51], v[0:15]
	v_mfma_f32_32x32x16_bf16 v[16:31], v[112:115], v[52:55], v[16:31]
	s_waitcnt lgkmcnt(13)
	v_mfma_f32_32x32x16_bf16 v[0:15], v[116:119], v[52:55], v[0:15]
	s_waitcnt lgkmcnt(12)
	v_mfma_f32_32x32x16_bf16 v[16:31], v[108:111], v[56:59], v[16:31]
	s_waitcnt lgkmcnt(10)
	v_mfma_f32_32x32x16_bf16 v[0:15], v[120:123], v[56:59], v[0:15]
	v_mfma_f32_32x32x16_bf16 v[16:31], v[100:103], v[60:63], v[16:31]
	s_waitcnt lgkmcnt(9)
	v_mfma_f32_32x32x16_bf16 v[0:15], v[104:107], v[60:63], v[0:15]
	s_waitcnt lgkmcnt(8)
	v_mfma_f32_32x32x16_bf16 v[48:63], v[64:67], v[80:83], v[32:47]
	s_waitcnt lgkmcnt(6)
	v_mfma_f32_32x32x16_bf16 v[32:47], v[72:75], v[80:83], v[32:47]
	v_mfma_f32_32x32x16_bf16 v[48:63], v[68:71], v[84:87], v[48:63]
	s_waitcnt lgkmcnt(5)
	v_mfma_f32_32x32x16_bf16 v[32:47], v[76:79], v[84:87], v[32:47]
	s_waitcnt lgkmcnt(4)
	v_mfma_f32_32x32x16_bf16 v[48:63], v[134:137], v[92:95], v[48:63]
	s_waitcnt lgkmcnt(2)
	v_mfma_f32_32x32x16_bf16 v[32:47], v[142:145], v[92:95], v[32:47]
	v_mfma_f32_32x32x16_bf16 v[48:63], v[138:141], v[88:91], v[48:63]
	s_waitcnt lgkmcnt(1)
	v_mfma_f32_32x32x16_bf16 v[32:47], v[146:149], v[88:91], v[32:47]
	s_setprio 0
	ds_read_b128 v[104:107], v199 offset:27648
	ds_read_b128 v[96:99], v199 offset:27680
	ds_read_b128 v[108:111], v199 offset:32256
	ds_read_b128 v[100:103], v199 offset:32288
	ds_read_b128 v[92:95], v199 offset:27712
	ds_read_b128 v[84:87], v199 offset:27744
	ds_read_b128 v[88:91], v199 offset:32320
	ds_read_b128 v[80:83], v199 offset:32352
	s_nop 1
	s_nop 0
	s_cmp_eq_u32 s98, 0
	s_cbranch_scc1 .Lstg_x_7
	s_waitcnt lgkmcnt(0)
	s_barrier
.Lstg_x_7:
.LBB0_344:
	s_nop 0
	v_exp_f32_e32 v64, v48
	v_exp_f32_e32 v65, v32
	v_exp_f32_e32 v66, v49
	v_exp_f32_e32 v67, v33
	v_exp_f32_e32 v68, v50
	v_exp_f32_e32 v69, v34
	v_exp_f32_e32 v70, v51
	v_exp_f32_e32 v71, v35
	v_add_f32_e32 v32, v65, v64
	v_exp_f32_e32 v72, v52
	v_exp_f32_e32 v73, v36
	v_add_f32_e32 v32, 0, v32
	v_add_f32_e32 v33, v67, v66
	v_exp_f32_e32 v74, v53
	v_exp_f32_e32 v75, v37
	v_add_f32_e32 v32, v33, v32
	v_add_f32_e32 v33, v69, v68
	v_exp_f32_e32 v54, v54
	v_exp_f32_e32 v76, v38
	v_add_f32_e32 v32, v33, v32
	v_add_f32_e32 v33, v71, v70
	v_exp_f32_e32 v55, v55
	v_exp_f32_e32 v77, v39
	v_add_f32_e32 v32, v33, v32
	v_add_f32_e32 v33, v73, v72
	v_add_f32_e32 v32, v33, v32
	v_add_f32_e32 v33, v75, v74
	v_add_f32_e32 v32, v33, v32
	v_add_f32_e32 v33, v76, v54
	v_add_f32_e32 v32, v33, v32
	v_add_f32_e32 v33, v77, v55
	v_add_f32_e32 v50, v33, v32
	v_exp_f32_e32 v33, v56
	v_exp_f32_e32 v35, v40
	v_exp_f32_e32 v32, v57
	v_exp_f32_e32 v34, v41
	v_exp_f32_e32 v49, v58
	v_exp_f32_e32 v37, v42
	v_exp_f32_e32 v48, v59
	v_exp_f32_e32 v36, v43
	v_pk_add_f32 v[38:39], v[34:35], v[32:33]
	v_exp_f32_e32 v51, v60
	v_add_f32_e32 v39, v39, v50
	v_add_f32_e32 v40, v38, v39
	v_pk_add_f32 v[38:39], v[36:37], v[48:49]
	v_exp_f32_e32 v50, v61
	v_add_f32_e32 v39, v39, v40
	v_add_f32_e32 v56, v38, v39
	v_exp_f32_e32 v39, v44
	v_exp_f32_e32 v38, v45
	v_exp_f32_e32 v53, v62
	v_exp_f32_e32 v41, v46
	v_exp_f32_e32 v52, v63
	v_exp_f32_e32 v40, v47
	v_pk_add_f32 v[42:43], v[38:39], v[50:51]
	s_nop 0
	v_add_f32_e32 v43, v43, v56
	v_add_f32_e32 v44, v42, v43
	v_pk_add_f32 v[42:43], v[40:41], v[52:53]
	s_nop 0
	v_add_f32_e32 v43, v43, v44
	v_add_f32_e32 v42, v42, v43
	v_add_f32_e32 v56, v132, v42
	v_pk_mov_b32 v[32:33], v[32:33], v[32:33] op_sel:[1,0]
	v_pk_mov_b32 v[34:35], v[34:35], v[34:35] op_sel:[1,0]
	v_pk_mov_b32 v[36:37], v[36:37], v[36:37] op_sel:[1,0]
	v_cvt_pk_bf16_f32 v42, v32, v33
	v_pk_mov_b32 v[32:33], v[48:49], v[48:49] op_sel:[1,0]
	v_cvt_pk_bf16_f32 v34, v34, v35
	v_cvt_pk_bf16_f32 v35, v36, v37
	v_pk_mov_b32 v[36:37], v[38:39], v[38:39] op_sel:[1,0]
	v_pk_mov_b32 v[38:39], v[40:41], v[40:41] op_sel:[1,0]
	v_cvt_pk_bf16_f32 v43, v32, v33
	v_pk_mov_b32 v[32:33], v[50:51], v[50:51] op_sel:[1,0]
	v_cvt_pk_bf16_f32 v36, v36, v37
	v_cvt_pk_bf16_f32 v37, v38, v39
	v_cvt_pk_bf16_f32 v38, v65, v67
	v_cvt_pk_bf16_f32 v39, v69, v71
	v_cvt_pk_bf16_f32 v44, v32, v33
	v_pk_mov_b32 v[32:33], v[52:53], v[52:53] op_sel:[1,0]
	v_cvt_pk_bf16_f32 v40, v73, v75
	v_cvt_pk_bf16_f32 v41, v76, v77
	v_cvt_pk_bf16_f32 v45, v32, v33
	v_cvt_pk_bf16_f32 v46, v64, v66
	v_cvt_pk_bf16_f32 v47, v68, v70
	v_cvt_pk_bf16_f32 v48, v72, v74
	v_cvt_pk_bf16_f32 v49, v54, v55
	s_setprio 1
	s_cmp_lg_u32 s98, 0
	s_cbranch_scc1 .Lstg_y_8
	s_waitcnt lgkmcnt(0)
	s_barrier

.LBB0_358:
	s_or_b64 exec, exec, s[8:9]
	v_mov_b32_e32 v135, v134
	v_pk_mul_f32 v[24:25], v[24:25], v[134:135]
	v_pk_mul_f32 v[26:27], v[26:27], v[134:135]
	v_pk_mul_f32 v[24:25], v[24:25], v[82:83]
	v_pk_mul_f32 v[26:27], v[26:27], v[80:81]
	v_cvt_pk_bf16_f32 v82, v24, v25
	v_add_u32_e32 v24, s0, v148
	v_ashrrev_i32_e32 v24, 6, v24
	v_cvt_f32_i32_e32 v24, v24
	v_cvt_pk_bf16_f32 v83, v26, v27
	v_and_b32_e32 v25, 63, v148
	v_cvt_f32_ubyte0_e32 v25, v25
	v_mul_f32_e32 v26, 0.15915494, v24
	v_cos_f32_e32 v146, v26
	v_sin_f32_e32 v158, v26
	v_mul_f32_e32 v26, v169, v24
	v_mul_f32_e32 v26, 0.15915494, v26
	v_cos_f32_e32 v147, v26
	v_sin_f32_e32 v159, v26
	v_mul_f32_e32 v26, v200, v24
	v_mul_f32_e32 v26, 0.15915494, v26
	v_cos_f32_e32 v148, v26
	v_sin_f32_e32 v162, v26
	v_mul_f32_e32 v26, v201, v24
	v_mul_f32_e32 v26, 0.15915494, v26
	v_cos_f32_e32 v149, v26
	v_sin_f32_e32 v163, v26
	v_mul_f32_e32 v26, v202, v24
	v_mul_f32_e32 v26, 0.15915494, v26
	v_cos_f32_e32 v152, v26
	v_sin_f32_e32 v190, v26
	v_mul_f32_e32 v26, v203, v24
	v_mul_f32_e32 v26, 0.15915494, v26
	v_cos_f32_e32 v153, v26
	v_sin_f32_e32 v191, v26
	v_mul_f32_e32 v26, v204, v24
	v_mul_f32_e32 v24, v205, v24
	v_mul_f32_e32 v24, 0.15915494, v24
	v_pk_mul_f32 v[30:31], v[30:31], v[134:135]
	v_cos_f32_e32 v151, v24
	v_sin_f32_e32 v195, v24
	v_mul_f32_e32 v24, 0.15915494, v25
	v_pk_mul_f32 v[30:31], v[30:31], v[142:143]
	v_cos_f32_e32 v142, v24
	v_sin_f32_e32 v160, v24
	v_mul_f32_e32 v24, v169, v25
	v_mul_f32_e32 v24, 0.15915494, v24
	v_cos_f32_e32 v143, v24
	v_sin_f32_e32 v161, v24
	v_mul_f32_e32 v24, v200, v25
	v_pk_mul_f32 v[28:29], v[28:29], v[134:135]
	v_mul_f32_e32 v24, 0.15915494, v24
	v_pk_mul_f32 v[28:29], v[28:29], v[144:145]
	v_cos_f32_e32 v144, v24
	v_sin_f32_e32 v164, v24
	v_mul_f32_e32 v24, v201, v25
	v_mul_f32_e32 v24, 0.15915494, v24
	v_cos_f32_e32 v145, v24
	v_sin_f32_e32 v165, v24
	v_mul_f32_e32 v24, v202, v25
	v_mul_f32_e32 v24, 0.15915494, v24
	v_cos_f32_e32 v154, v24
	v_sin_f32_e32 v166, v24
	v_mul_f32_e32 v24, v203, v25
	v_mul_f32_e32 v24, 0.15915494, v24
	v_cos_f32_e32 v155, v24
	v_sin_f32_e32 v167, v24
	v_mul_f32_e32 v24, v204, v25
	v_mul_f32_e32 v24, 0.15915494, v24
	v_cos_f32_e32 v156, v24
	v_sin_f32_e32 v196, v24
	v_mul_f32_e32 v24, v205, v25
	v_pk_mul_f32 v[20:21], v[20:21], v[134:135]
	v_pk_mul_f32 v[22:23], v[22:23], v[134:135]
	v_pk_mul_f32 v[16:17], v[16:17], v[134:135]
	v_pk_mul_f32 v[18:19], v[18:19], v[134:135]
	v_cvt_pk_bf16_f32 v80, v28, v29
	v_cvt_pk_bf16_f32 v81, v30, v31
	v_mul_f32_e32 v26, 0.15915494, v26
	v_mul_f32_e32 v24, 0.15915494, v24
	v_pk_mul_f32 v[20:21], v[20:21], v[140:141]
	v_pk_mul_f32 v[22:23], v[22:23], v[138:139]
	v_pk_mul_f32 v[16:17], v[16:17], v[86:87]
	v_pk_mul_f32 v[18:19], v[18:19], v[84:85]
	v_cos_f32_e32 v150, v26
	v_sin_f32_e32 v194, v26
	v_cos_f32_e32 v157, v24
	v_sin_f32_e32 v197, v24
	v_cvt_pk_bf16_f32 v84, v20, v21
	v_cvt_pk_bf16_f32 v85, v22, v23
	v_cvt_pk_bf16_f32 v86, v16, v17
	v_cvt_pk_bf16_f32 v87, v18, v19
	s_waitcnt lgkmcnt(5)
	v_mfma_f32_32x32x16_bf16 v[16:31], v[72:75], v[80:83], v[0:15]
	v_mul_f32_e64 v32, v32, v134
	v_mul_f32_e64 v33, v33, v135
	v_mul_f32_e64 v36, v36, v134
	v_mul_f32_e64 v37, v37, v135
	v_mul_f32_e64 v32, v32, v78
	v_mul_f32_e64 v33, v33, v79
	v_pk_mul_f32 v[44:45], v[44:45], v[134:135]
	v_pk_mul_f32 v[36:37], v[36:37], v[94:95]
	v_cvt_pk_bf16_f32 v94, v32, v33
	v_pk_mul_f32 v[32:33], v[158:159], v[136:137]
	s_waitcnt lgkmcnt(3)
	v_mfma_f32_32x32x16_bf16 v[0:15], v[68:71], v[80:83], v[0:15]
	v_cmp_eq_u32_e32 vcc, 0, v219
	v_mul_f32_e64 v44, v44, v98
	v_mul_f32_e64 v45, v45, v99
	v_mul_f32_e64 v42, v42, v134
	v_mul_f32_e64 v43, v43, v135
	v_cndmask_b32_e64 v33, v33, -v33, vcc
	v_cndmask_b32_e64 v32, v32, -v32, vcc
	v_pk_mul_f32 v[46:47], v[46:47], v[134:135]
	v_pk_mul_f32 v[40:41], v[40:41], v[134:135]
	v_mfma_f32_32x32x16_bf16 v[16:31], v[64:67], v[84:87], v[16:31]
	v_mul_f32_e64 v42, v42, v88
	v_mul_f32_e64 v43, v43, v89
	v_cvt_pk_bf16_f32 v88, v44, v45
	v_mul_f32_e64 v34, v34, v134
	v_mul_f32_e64 v35, v35, v135
	v_pk_fma_f32 v[44:45], v[146:147], v[128:129], v[32:33]
	v_pk_mul_f32 v[32:33], v[162:163], v[132:133]
	v_pk_mul_f32 v[46:47], v[46:47], v[96:97]
	v_pk_mul_f32 v[40:41], v[40:41], v[90:91]
	s_waitcnt lgkmcnt(1)
	v_mfma_f32_32x32x16_bf16 v[0:15], v[60:63], v[84:87], v[0:15]
	v_mul_f32_e64 v34, v34, v76
	v_mul_f32_e64 v35, v35, v77
	v_cndmask_b32_e64 v33, v33, -v33, vcc
	v_cndmask_b32_e64 v32, v32, -v32, vcc
	v_cvt_pk_bf16_f32 v89, v46, v47
	v_cvt_pk_bf16_f32 v90, v40, v41
	v_cvt_pk_bf16_f32 v91, v42, v43
	v_cvt_pk_bf16_f32 v95, v34, v35
	v_pk_fma_f32 v[46:47], v[148:149], v[122:123], v[32:33]
	ds_read_b128 v[32:35], v208 offset:96
	v_pk_mul_f32 v[38:39], v[38:39], v[134:135]
	v_mfma_f32_32x32x16_bf16 v[16:31], v[56:59], v[88:91], v[16:31]
	v_mul_f32_e64 v38, v38, v92
	v_mul_f32_e64 v39, v39, v93
	v_cvt_pk_bf16_f32 v92, v36, v37
	v_mul_f32_e64 v36, v190, v130
	v_mul_f32_e64 v37, v191, v131
	v_cvt_pk_bf16_f32 v93, v38, v39
	v_cndmask_b32_e64 v37, v37, -v37, vcc
	v_cndmask_b32_e64 v36, v36, -v36, vcc
	v_cvt_pk_bf16_f32 v96, v44, v45
	s_waitcnt lgkmcnt(1)
	v_mfma_f32_32x32x16_bf16 v[0:15], v[52:55], v[88:91], v[0:15]
	v_fma_f32 v52, v152, v118, v36
	v_fma_f32 v53, v153, v119, v37
	v_mul_f32_e64 v36, v194, v126
	v_mul_f32_e64 v37, v195, v127
	v_mul_f32_e64 v44, v160, v124
	v_mul_f32_e64 v45, v161, v125
	v_cndmask_b32_e64 v55, v37, -v37, vcc
	v_cndmask_b32_e64 v54, v36, -v36, vcc
	ds_read_b128 v[36:39], v208 offset:6752
	ds_read_b128 v[40:43], v208 offset:128
	v_cvt_pk_bf16_f32 v97, v46, v47
	s_waitcnt lgkmcnt(2)
	v_mfma_f32_32x32x16_bf16 v[16:31], v[32:35], v[92:95], v[16:31]
	v_fma_f32 v32, v150, v112, v54
	v_fma_f32 v33, v151, v113, v55
	v_cvt_pk_bf16_f32 v98, v52, v53
	v_cvt_pk_bf16_f32 v99, v32, v33
	ds_read_b128 v[32:35], v208 offset:160
	v_pk_mul_f32 v[54:55], v[196:197], v[114:115]
	s_waitcnt lgkmcnt(2)
	v_mfma_f32_32x32x16_bf16 v[0:15], v[36:39], v[92:95], v[0:15]
	v_cndmask_b32_e64 v37, v45, -v45, vcc
	v_cndmask_b32_e64 v36, v44, -v44, vcc
	v_fma_f32 v44, v142, v110, v36
	v_fma_f32 v45, v143, v111, v37
	v_mul_f32_e64 v36, v164, v120
	v_mul_f32_e64 v37, v165, v121
	v_cndmask_b32_e64 v47, v37, -v37, vcc
	v_cndmask_b32_e64 v46, v36, -v36, vcc
	ds_read_b128 v[36:39], v208 offset:6784
	s_waitcnt lgkmcnt(2)
	v_mfma_f32_32x32x16_bf16 v[16:31], v[40:43], v[96:99], v[16:31]
	v_mul_f32_e64 v40, v166, v116
	v_mul_f32_e64 v41, v167, v117
	v_fma_f32 v46, v144, v108, v46
	v_fma_f32 v47, v145, v109, v47
	v_cndmask_b32_e64 v41, v41, -v41, vcc
	v_cndmask_b32_e64 v40, v40, -v40, vcc
	v_pk_fma_f32 v[52:53], v[154:155], v[102:103], v[40:41]
	ds_read_b128 v[40:43], v208 offset:6816
	v_cvt_pk_bf16_f32 v102, v52, v53
	s_waitcnt lgkmcnt(1)
	v_mfma_f32_32x32x16_bf16 v[0:15], v[36:39], v[96:99], v[0:15]
	v_cndmask_b32_e64 v37, v55, -v55, vcc
	v_cndmask_b32_e64 v36, v54, -v54, vcc
	global_load_dwordx4 v[52:55], v[192:193], off offset:256
	v_fma_f32 v36, v156, v100, v36
	v_fma_f32 v37, v157, v101, v37
	v_cvt_pk_bf16_f32 v100, v44, v45
	v_cvt_pk_bf16_f32 v101, v46, v47
	v_cvt_pk_bf16_f32 v103, v36, v37
	s_nop 1
	v_mfma_f32_32x32x16_bf16 v[16:31], v[32:35], v[100:103], v[16:31]
	s_waitcnt lgkmcnt(0)
	v_mfma_f32_32x32x16_bf16 v[0:15], v[40:43], v[100:103], v[0:15]
	s_setprio 0
	ds_read_b128 v[64:67], v209 offset:39936
	ds_read_b128 v[68:71], v209 offset:39968
	ds_read_b128 v[72:75], v209 offset:44544
	ds_read_b128 v[76:79], v209 offset:44576
	ds_read_b128 v[108:111], v209 offset:40000
	ds_read_b128 v[112:115], v209 offset:40032
	ds_read_b128 v[116:119], v209 offset:44608
	ds_read_b128 v[56:59], v209 offset:44640
	s_nop 3
	v_mov_b32_e32 v33, s100
	s_cmp_eq_u32 s98, 0
	s_cbranch_scc1 .Lstg_x_9
	s_waitcnt lgkmcnt(0)
	s_barrier
.Lstg_x_9:
	v_sub_f32_e32 v0, v0, v33
	v_sub_f32_e32 v32, v7, v33
	v_sub_f32_e32 v7, v16, v33
	v_sub_f32_e32 v1, v1, v33
	v_sub_f32_e32 v34, v8, v33
	v_sub_f32_e32 v37, v11, v33
	v_sub_f32_e32 v8, v17, v33
	v_sub_f32_e32 v11, v20, v33
	v_sub_f32_e32 v20, v28, v33
	v_exp_f32_e32 v28, v7
	v_exp_f32_e32 v60, v0
	v_sub_f32_e32 v39, v13, v33
	v_sub_f32_e32 v40, v14, v33
	v_sub_f32_e32 v13, v22, v33
	v_sub_f32_e32 v14, v23, v33
	v_sub_f32_e32 v22, v29, v33
	v_sub_f32_e32 v23, v30, v33
	v_exp_f32_e32 v29, v8
	v_exp_f32_e32 v30, v1
	v_sub_f32_e32 v2, v2, v33
	v_sub_f32_e32 v35, v9, v33
	v_sub_f32_e32 v9, v18, v33
	v_sub_f32_e32 v3, v3, v33
	v_sub_f32_e32 v36, v10, v33
	v_sub_f32_e32 v41, v15, v33
	v_sub_f32_e32 v10, v19, v33
	v_sub_f32_e32 v15, v24, v33
	v_sub_f32_e32 v24, v31, v33
	v_add_f32_e32 v0, v28, v60
	v_exp_f32_e32 v31, v9
	v_exp_f32_e32 v61, v2
	v_sub_f32_e32 v4, v4, v33
	v_sub_f32_e32 v5, v5, v33
	v_sub_f32_e32 v38, v12, v33
	v_sub_f32_e32 v12, v21, v33
	v_add_f32_e32 v0, 0, v0
	v_add_f32_e32 v1, v29, v30
	v_exp_f32_e32 v62, v10
	v_exp_f32_e32 v63, v3
	v_add_f32_e32 v7, v1, v0
	v_exp_f32_e32 v1, v11
	v_exp_f32_e32 v3, v4
	v_exp_f32_e32 v0, v12
	v_exp_f32_e32 v2, v5
	v_add_f32_e32 v8, v31, v61
	v_add_f32_e32 v4, v8, v7
	v_add_f32_e32 v5, v62, v63
	v_sub_f32_e32 v6, v6, v33
	v_add_f32_e32 v7, v5, v4
	v_pk_add_f32 v[4:5], v[0:1], v[2:3]
	v_exp_f32_e32 v9, v6
	v_add_f32_e32 v5, v5, v7
	v_exp_f32_e32 v7, v13
	v_exp_f32_e32 v6, v14
	v_exp_f32_e32 v8, v32
	v_sub_f32_e32 v16, v25, v33
	v_pk_mov_b32 v[10:11], v[0:1], v[0:1] op_sel:[1,0]
	v_pk_mov_b32 v[12:13], v[2:3], v[2:3] op_sel:[1,0]
	v_add_f32_e32 v2, v4, v5
	v_pk_add_f32 v[0:1], v[6:7], v[8:9]
	v_exp_f32_e32 v3, v15
	v_add_f32_e32 v1, v1, v2
	v_exp_f32_e32 v5, v34
	v_exp_f32_e32 v2, v16
	v_exp_f32_e32 v4, v35
	v_sub_f32_e32 v17, v26, v33
	v_sub_f32_e32 v18, v27, v33
	v_add_f32_e32 v14, v0, v1
	v_pk_add_f32 v[0:1], v[2:3], v[4:5]
	v_exp_f32_e32 v15, v17
	v_add_f32_e32 v1, v1, v14
	v_exp_f32_e32 v17, v36
	v_exp_f32_e32 v14, v18
	v_exp_f32_e32 v16, v37
	v_pk_mov_b32 v[18:19], v[2:3], v[2:3] op_sel:[1,0]
	v_add_f32_e32 v2, v0, v1
	v_exp_f32_e32 v3, v20
	v_pk_add_f32 v[0:1], v[14:15], v[16:17]
	v_exp_f32_e32 v21, v38
	v_add_f32_e32 v1, v1, v2
	v_exp_f32_e32 v2, v22
	v_exp_f32_e32 v20, v39
	v_add_f32_e32 v22, v0, v1
	v_exp_f32_e32 v23, v23
	v_exp_f32_e32 v25, v40
	v_pk_add_f32 v[0:1], v[2:3], v[20:21]
	v_pk_mov_b32 v[26:27], v[2:3], v[2:3] op_sel:[1,0]
	v_add_f32_e32 v1, v1, v22
	v_exp_f32_e32 v22, v24
	v_exp_f32_e32 v24, v41
	v_add_f32_e32 v2, v0, v1
	v_pk_mov_b32 v[6:7], v[6:7], v[6:7] op_sel:[1,0]
	v_pk_mov_b32 v[8:9], v[8:9], v[8:9] op_sel:[1,0]
	v_pk_add_f32 v[0:1], v[22:23], v[24:25]
	v_pk_mov_b32 v[4:5], v[4:5], v[4:5] op_sel:[1,0]
	v_add_f32_e32 v1, v1, v2
	v_add_f32_e32 v32, v0, v1
	v_pk_add_f32 v[190:191], v[32:33], 0 op_sel_hi:[1,0]
	v_pk_mov_b32 v[14:15], v[14:15], v[14:15] op_sel:[1,0]
	v_xor_b32_e32 v32, 0x80000000, v191
	v_pk_mov_b32 v[16:17], v[16:17], v[16:17] op_sel:[1,0]
	v_pk_mov_b32 v[20:21], v[20:21], v[20:21] op_sel:[1,0]
	v_pk_mov_b32 v[22:23], v[22:23], v[22:23] op_sel:[1,0]
	v_pk_mov_b32 v[24:25], v[24:25], v[24:25] op_sel:[1,0]
	v_mov_b32_e32 v33, v32
	v_mov_b32_e32 v34, v32
	v_mov_b32_e32 v35, v32
	v_mov_b32_e32 v36, v32
	v_mov_b32_e32 v37, v32
	v_mov_b32_e32 v38, v32
	v_mov_b32_e32 v39, v32
	v_mov_b32_e32 v40, v32
	v_mov_b32_e32 v41, v32
	v_mov_b32_e32 v42, v32
	v_mov_b32_e32 v43, v32
	v_mov_b32_e32 v44, v32
	v_mov_b32_e32 v45, v32
	v_mov_b32_e32 v46, v32
	v_mov_b32_e32 v47, v32
	v_cvt_pk_bf16_f32 v0, v28, v29
	v_cvt_pk_bf16_f32 v1, v31, v62
	v_cvt_pk_bf16_f32 v2, v10, v11
	v_cvt_pk_bf16_f32 v3, v6, v7
	v_cvt_pk_bf16_f32 v120, v18, v19
	v_cvt_pk_bf16_f32 v121, v14, v15
	v_cvt_pk_bf16_f32 v122, v26, v27
	v_cvt_pk_bf16_f32 v123, v22, v23
	v_cvt_pk_bf16_f32 v124, v60, v30
	v_cvt_pk_bf16_f32 v125, v61, v63
	v_cvt_pk_bf16_f32 v126, v12, v13
	v_cvt_pk_bf16_f32 v127, v8, v9
	v_cvt_pk_bf16_f32 v128, v4, v5
	v_cvt_pk_bf16_f32 v129, v16, v17
	v_cvt_pk_bf16_f32 v130, v20, v21
	v_cvt_pk_bf16_f32 v131, v24, v25
	s_setprio 1
	s_cmp_lg_u32 s98, 0
	s_cbranch_scc1 .Lstg_y_10
	s_waitcnt lgkmcnt(0)
	s_barrier

.LBB0_363:
	s_or_b64 exec, exec, s[8:9]
	s_waitcnt lgkmcnt(7)
	v_mfma_f32_32x32x16_bf16 v[64:79], v[60:63], v[80:83], v[32:47]
	s_mul_i32 s8, s42, 0x3400
	v_add_u32_e32 v124, s8, v208
	ds_read_b128 v[108:111], v124 offset:96
	ds_read_b128 v[116:119], v124 offset:128
	s_waitcnt lgkmcnt(7)
	v_mfma_f32_32x32x16_bf16 v[48:63], v[164:167], v[80:83], v[32:47]
	v_mfma_f32_32x32x16_bf16 v[64:79], v[156:159], v[84:87], v[64:79]
	s_waitcnt lgkmcnt(5)
	v_mfma_f32_32x32x16_bf16 v[48:63], v[160:163], v[84:87], v[48:63]
	v_mfma_f32_32x32x16_bf16 v[64:79], v[152:155], v[88:91], v[64:79]
	s_waitcnt lgkmcnt(4)
	v_mfma_f32_32x32x16_bf16 v[48:63], v[148:151], v[88:91], v[48:63]
	s_waitcnt lgkmcnt(1)
	v_mfma_f32_32x32x16_bf16 v[64:79], v[108:111], v[92:95], v[64:79]
	ds_read_b128 v[108:111], v124 offset:6752
	ds_read_b128 v[120:123], v124 offset:160
	s_waitcnt lgkmcnt(1)
	v_mfma_f32_32x32x16_bf16 v[48:63], v[108:111], v[92:95], v[48:63]
	v_mfma_f32_32x32x16_bf16 v[64:79], v[116:119], v[96:99], v[64:79]
	ds_read_b128 v[108:111], v124 offset:6784
	ds_read_b128 v[116:119], v124 offset:6816
	s_waitcnt lgkmcnt(1)
	v_mfma_f32_32x32x16_bf16 v[48:63], v[108:111], v[96:99], v[48:63]
	global_load_dwordx4 v[108:111], v[196:197], off
	v_mfma_f32_32x32x16_bf16 v[64:79], v[120:123], v[100:103], v[64:79]
	s_waitcnt lgkmcnt(0)
	v_mfma_f32_32x32x16_bf16 v[48:63], v[116:119], v[100:103], v[48:63]
	s_setprio 0
	s_and_b32 s72, 1, s33
	s_cselect_b32 s8, 0, 0x2400
	v_add_u32_e32 v116, s8, v209
	ds_read_b128 v[140:143], v116 offset:39936
	ds_read_b128 v[128:131], v116 offset:39968
	ds_read_b128 v[144:147], v116 offset:44544
	ds_read_b128 v[132:135], v116 offset:44576
	ds_read_b128 v[124:127], v116 offset:40000
	ds_read_b128 v[120:123], v116 offset:40032
	ds_read_b128 v[136:139], v116 offset:44608
	ds_read_b128 v[116:119], v116 offset:44640
.LBB0_365:
	v_exp_f32_e32 v64, v64
	v_exp_f32_e32 v219, v48
	v_exp_f32_e32 v48, v65
	v_exp_f32_e32 v220, v49
	v_exp_f32_e32 v49, v66
	v_exp_f32_e32 v221, v50
	v_exp_f32_e32 v50, v67
	v_exp_f32_e32 v222, v51
	s_cmp_eq_u32 s98, 0
	s_cbranch_scc1 .Lstg_x_11
	s_waitcnt lgkmcnt(0)
	s_barrier
.Lstg_x_11:
	v_exp_f32_e32 v51, v68
	v_exp_f32_e32 v68, v52
	v_exp_f32_e32 v52, v69
	v_exp_f32_e32 v69, v53
	v_exp_f32_e32 v53, v70
	v_exp_f32_e32 v70, v54
	v_exp_f32_e32 v54, v71
	v_exp_f32_e32 v71, v55
	v_exp_f32_e32 v55, v72
	v_exp_f32_e32 v72, v56
	v_exp_f32_e32 v56, v73
	v_exp_f32_e32 v73, v57
	v_exp_f32_e32 v57, v74
	v_exp_f32_e32 v74, v58
	v_exp_f32_e32 v58, v75
	v_exp_f32_e32 v75, v59
	v_exp_f32_e32 v59, v76
	v_exp_f32_e32 v76, v60
	v_exp_f32_e32 v65, v77
	v_exp_f32_e32 v77, v61
	v_exp_f32_e32 v66, v78
	v_exp_f32_e32 v78, v62
	v_exp_f32_e32 v67, v79
	v_exp_f32_e32 v79, v63
	v_cvt_pk_bf16_f32 v224, v64, v48
	v_cvt_pk_bf16_f32 v225, v49, v50
	v_cvt_pk_bf16_f32 v226, v51, v52
	v_cvt_pk_bf16_f32 v227, v53, v54
	v_cvt_pk_bf16_f32 v228, v55, v56
	v_cvt_pk_bf16_f32 v229, v57, v58
	v_cvt_pk_bf16_f32 v230, v59, v65
	v_cvt_pk_bf16_f32 v231, v66, v67
	v_cvt_pk_bf16_f32 v232, v219, v220
	v_cvt_pk_bf16_f32 v233, v221, v222
	v_cvt_pk_bf16_f32 v234, v68, v69
	v_cvt_pk_bf16_f32 v235, v70, v71
	v_cvt_pk_bf16_f32 v236, v72, v73
	v_cvt_pk_bf16_f32 v237, v74, v75
	v_cvt_pk_bf16_f32 v238, v76, v77
	v_cvt_pk_bf16_f32 v239, v78, v79
	s_setprio 1
	s_cmp_lg_u32 s98, 0
	s_cbranch_scc1 .Lstg_y_12
	s_waitcnt lgkmcnt(0)
	s_barrier

.LBB0_369:
	s_waitcnt lgkmcnt(7)
	v_mfma_f32_32x32x16_bf16 v[64:79], v[60:63], v[80:83], v[32:47]
	ds_read_b128 v[104:107], v189 offset:96
	ds_read_b128 v[108:111], v189 offset:128
	s_waitcnt lgkmcnt(7)
	v_mfma_f32_32x32x16_bf16 v[48:63], v[164:167], v[80:83], v[32:47]
	v_mfma_f32_32x32x16_bf16 v[64:79], v[156:159], v[84:87], v[64:79]
	s_waitcnt lgkmcnt(5)
	v_mfma_f32_32x32x16_bf16 v[48:63], v[160:163], v[84:87], v[48:63]
	v_mfma_f32_32x32x16_bf16 v[64:79], v[152:155], v[88:91], v[64:79]
	s_waitcnt lgkmcnt(4)
	v_mfma_f32_32x32x16_bf16 v[48:63], v[148:151], v[88:91], v[48:63]
	s_waitcnt lgkmcnt(1)
	v_mfma_f32_32x32x16_bf16 v[64:79], v[104:107], v[92:95], v[64:79]
	ds_read_b128 v[104:107], v189 offset:6752
	ds_read_b128 v[112:115], v189 offset:160
	s_waitcnt lgkmcnt(1)
	v_mfma_f32_32x32x16_bf16 v[48:63], v[104:107], v[92:95], v[48:63]
	v_mfma_f32_32x32x16_bf16 v[64:79], v[108:111], v[96:99], v[64:79]
	ds_read_b128 v[104:107], v189 offset:6784
	ds_read_b128 v[108:111], v189 offset:6816
	s_waitcnt lgkmcnt(1)
	v_mfma_f32_32x32x16_bf16 v[48:63], v[104:107], v[96:99], v[48:63]
	v_mfma_f32_32x32x16_bf16 v[64:79], v[112:115], v[100:103], v[64:79]
	s_waitcnt lgkmcnt(0)
	v_mfma_f32_32x32x16_bf16 v[48:63], v[108:111], v[100:103], v[48:63]
	s_setprio 0
	ds_read_b128 v[132:135], v209 offset:39936
	ds_read_b128 v[120:123], v209 offset:39968
	ds_read_b128 v[136:139], v209 offset:44544
	ds_read_b128 v[124:127], v209 offset:44576
	ds_read_b128 v[116:119], v209 offset:40000
	ds_read_b128 v[108:111], v209 offset:40032
	ds_read_b128 v[128:131], v209 offset:44608
	ds_read_b128 v[112:115], v209 offset:44640
	s_nop 1
	s_nop 0
	s_cmp_eq_u32 s98, 0
	s_cbranch_scc1 .Lstg_x_13
	s_waitcnt lgkmcnt(0)
	s_barrier
.Lstg_x_13:
.LBB0_371:
	v_exp_f32_e32 v141, v64
	v_exp_f32_e32 v142, v48
	v_exp_f32_e32 v143, v65
	v_exp_f32_e32 v144, v49
	v_exp_f32_e32 v145, v66
	v_add_f32_e32 v48, v142, v141
	v_exp_f32_e32 v146, v50
	v_add_f32_e32 v48, 0, v48
	v_add_f32_e32 v49, v144, v143
	v_exp_f32_e32 v147, v67
	v_exp_f32_e32 v148, v51
	v_add_f32_e32 v64, v49, v48
	v_exp_f32_e32 v49, v68
	v_exp_f32_e32 v51, v52
	v_exp_f32_e32 v48, v69
	v_exp_f32_e32 v50, v53
	v_add_f32_e32 v65, v146, v145
	v_add_f32_e32 v52, v65, v64
	v_add_f32_e32 v53, v148, v147
	v_add_f32_e32 v64, v53, v52
	v_pk_add_f32 v[52:53], v[50:51], v[48:49]
	v_exp_f32_e32 v65, v70
	v_add_f32_e32 v53, v53, v64
	v_exp_f32_e32 v67, v54
	v_exp_f32_e32 v64, v71
	v_exp_f32_e32 v66, v55
	v_pk_mov_b32 v[54:55], v[48:49], v[48:49] op_sel:[1,0]
	v_pk_mov_b32 v[68:69], v[50:51], v[50:51] op_sel:[1,0]
	v_add_f32_e32 v50, v52, v53
	v_pk_add_f32 v[48:49], v[66:67], v[64:65]
	v_exp_f32_e32 v51, v72
	v_add_f32_e32 v49, v49, v50
	v_exp_f32_e32 v53, v56
	v_exp_f32_e32 v50, v73
	v_exp_f32_e32 v52, v57
	v_pk_mov_b32 v[56:57], v[64:65], v[64:65] op_sel:[1,0]
	v_pk_mov_b32 v[64:65], v[66:67], v[66:67] op_sel:[1,0]
	v_add_f32_e32 v66, v48, v49
	v_pk_add_f32 v[48:49], v[52:53], v[50:51]
	v_exp_f32_e32 v67, v74
	v_add_f32_e32 v49, v49, v66
	v_exp_f32_e32 v71, v58
	v_exp_f32_e32 v66, v75
	v_exp_f32_e32 v70, v59
	v_pk_mov_b32 v[58:59], v[50:51], v[50:51] op_sel:[1,0]
	v_add_f32_e32 v50, v48, v49
	v_pk_mov_b32 v[72:73], v[52:53], v[52:53] op_sel:[1,0]
	v_pk_add_f32 v[48:49], v[70:71], v[66:67]
	v_exp_f32_e32 v51, v76
	v_add_f32_e32 v49, v49, v50
	v_exp_f32_e32 v53, v60
	v_exp_f32_e32 v50, v77
	v_exp_f32_e32 v52, v61
	v_pk_mov_b32 v[60:61], v[66:67], v[66:67] op_sel:[1,0]
	v_pk_mov_b32 v[66:67], v[70:71], v[70:71] op_sel:[1,0]
	v_add_f32_e32 v70, v48, v49
	v_pk_add_f32 v[48:49], v[52:53], v[50:51]
	v_exp_f32_e32 v71, v78
	v_add_f32_e32 v49, v49, v70
	v_exp_f32_e32 v75, v62
	v_exp_f32_e32 v70, v79
	v_exp_f32_e32 v74, v63
	v_pk_mov_b32 v[62:63], v[50:51], v[50:51] op_sel:[1,0]
	v_add_f32_e32 v50, v48, v49
	v_pk_mov_b32 v[76:77], v[52:53], v[52:53] op_sel:[1,0]
	v_pk_add_f32 v[48:49], v[74:75], v[70:71]
	v_pk_mov_b32 v[70:71], v[70:71], v[70:71] op_sel:[1,0]
	v_add_f32_e32 v49, v49, v50
	v_pk_mov_b32 v[74:75], v[74:75], v[74:75] op_sel:[1,0]
	v_add_f32_e32 v48, v48, v49
	v_add_f32_e32 v140, v190, v48
	v_cvt_pk_bf16_f32 v48, v141, v143
	v_cvt_pk_bf16_f32 v49, v145, v147
	v_cvt_pk_bf16_f32 v50, v54, v55
	v_cvt_pk_bf16_f32 v51, v56, v57
	v_cvt_pk_bf16_f32 v52, v58, v59
	v_cvt_pk_bf16_f32 v53, v60, v61
	v_cvt_pk_bf16_f32 v54, v62, v63
	v_cvt_pk_bf16_f32 v55, v70, v71
	v_cvt_pk_bf16_f32 v56, v142, v144
	v_cvt_pk_bf16_f32 v57, v146, v148
	v_cvt_pk_bf16_f32 v58, v68, v69
	v_cvt_pk_bf16_f32 v59, v64, v65
	v_cvt_pk_bf16_f32 v60, v72, v73
	v_cvt_pk_bf16_f32 v61, v66, v67
	v_cvt_pk_bf16_f32 v62, v76, v77
	v_cvt_pk_bf16_f32 v63, v74, v75
	s_setprio 1
	s_cmp_lg_u32 s98, 0
	s_cbranch_scc1 .Lstg_y_14
	s_waitcnt lgkmcnt(0)
	s_barrier
.Lstg_y_14:
	v_add_u32_e32 v141, s44, v208
	ds_read_b128 v[64:67], v141
	ds_read_b128 v[68:71], v141 offset:32
	ds_read_b128 v[72:75], v141 offset:6656
	ds_read_b128 v[76:79], v141 offset:64
	ds_read_b128 v[142:145], v141 offset:6688
	ds_read_b128 v[146:149], v141 offset:6720
	s_waitcnt lgkmcnt(13)
	v_mfma_f32_32x32x16_bf16 v[16:31], v[132:135], v[48:51], v[16:31]
	s_waitcnt lgkmcnt(12)
	v_mfma_f32_32x32x16_bf16 v[0:15], v[136:139], v[48:51], v[0:15]
	v_mfma_f32_32x32x16_bf16 v[16:31], v[120:123], v[52:55], v[16:31]
	s_waitcnt lgkmcnt(11)
	v_mfma_f32_32x32x16_bf16 v[0:15], v[124:127], v[52:55], v[0:15]
	s_waitcnt lgkmcnt(10)
	v_mfma_f32_32x32x16_bf16 v[16:31], v[116:119], v[56:59], v[16:31]
	s_waitcnt lgkmcnt(8)
	v_mfma_f32_32x32x16_bf16 v[0:15], v[128:131], v[56:59], v[0:15]
	v_mfma_f32_32x32x16_bf16 v[16:31], v[108:111], v[60:63], v[16:31]
	s_waitcnt lgkmcnt(7)
	v_mfma_f32_32x32x16_bf16 v[0:15], v[112:115], v[60:63], v[0:15]
	s_waitcnt lgkmcnt(6)
	v_mfma_f32_32x32x16_bf16 v[48:63], v[64:67], v[80:83], v[32:47]
	s_waitcnt lgkmcnt(4)
	v_mfma_f32_32x32x16_bf16 v[32:47], v[72:75], v[80:83], v[32:47]
	v_mfma_f32_32x32x16_bf16 v[48:63], v[68:71], v[84:87], v[48:63]
	ds_read_b128 v[64:67], v141 offset:96
	ds_read_b128 v[68:71], v141 offset:128
	s_waitcnt lgkmcnt(4)
	v_mfma_f32_32x32x16_bf16 v[32:47], v[142:145], v[84:87], v[32:47]
	v_mfma_f32_32x32x16_bf16 v[48:63], v[76:79], v[88:91], v[48:63]
	s_waitcnt lgkmcnt(3)
	v_mfma_f32_32x32x16_bf16 v[32:47], v[146:149], v[88:91], v[32:47]
	s_waitcnt lgkmcnt(1)
	v_mfma_f32_32x32x16_bf16 v[48:63], v[64:67], v[92:95], v[48:63]
	ds_read_b128 v[64:67], v141 offset:6752
	ds_read_b128 v[72:75], v141 offset:160
	s_waitcnt lgkmcnt(1)
	v_mfma_f32_32x32x16_bf16 v[32:47], v[64:67], v[92:95], v[32:47]
	v_mfma_f32_32x32x16_bf16 v[48:63], v[68:71], v[96:99], v[48:63]
	ds_read_b128 v[64:67], v141 offset:6784
	ds_read_b128 v[68:71], v141 offset:6816
	s_waitcnt lgkmcnt(1)
	v_mfma_f32_32x32x16_bf16 v[32:47], v[64:67], v[96:99], v[32:47]
	v_mfma_f32_32x32x16_bf16 v[48:63], v[72:75], v[100:103], v[48:63]
	s_waitcnt lgkmcnt(0)
	v_mfma_f32_32x32x16_bf16 v[32:47], v[68:71], v[100:103], v[32:47]
	s_setprio 0
	ds_read_b128 v[104:107], v209 offset:49152
	ds_read_b128 v[96:99], v209 offset:49184
	ds_read_b128 v[108:111], v209 offset:53760
	ds_read_b128 v[100:103], v209 offset:53792
	ds_read_b128 v[92:95], v209 offset:49216
	ds_read_b128 v[84:87], v209 offset:49248
	ds_read_b128 v[88:91], v209 offset:53824
	ds_read_b128 v[80:83], v209 offset:53856
	s_nop 1
	s_nop 0
	s_cmp_eq_u32 s98, 0
	s_cbranch_scc1 .Lstg_x_15
	s_waitcnt lgkmcnt(0)
	s_barrier
.Lstg_x_15:
.LBB0_373:
	s_nop 0
	v_exp_f32_e32 v64, v48
	v_exp_f32_e32 v65, v32
	v_exp_f32_e32 v66, v49
	v_exp_f32_e32 v67, v33
	v_exp_f32_e32 v68, v50
	v_exp_f32_e32 v69, v34
	v_exp_f32_e32 v70, v51
	v_exp_f32_e32 v71, v35
	v_add_f32_e32 v32, v65, v64
	v_exp_f32_e32 v72, v52
	v_exp_f32_e32 v73, v36
	v_add_f32_e32 v32, 0, v32
	v_add_f32_e32 v33, v67, v66
	v_exp_f32_e32 v74, v53
	v_exp_f32_e32 v75, v37
	v_add_f32_e32 v32, v33, v32
	v_add_f32_e32 v33, v69, v68
	v_exp_f32_e32 v54, v54
	v_exp_f32_e32 v76, v38
	v_add_f32_e32 v32, v33, v32
	v_add_f32_e32 v33, v71, v70
	v_exp_f32_e32 v55, v55
	v_exp_f32_e32 v77, v39
	v_add_f32_e32 v32, v33, v32
	v_add_f32_e32 v33, v73, v72
	v_add_f32_e32 v32, v33, v32
	v_add_f32_e32 v33, v75, v74
	v_add_f32_e32 v32, v33, v32
	v_add_f32_e32 v33, v76, v54
	v_add_f32_e32 v32, v33, v32
	v_add_f32_e32 v33, v77, v55
	v_add_f32_e32 v50, v33, v32
	v_exp_f32_e32 v33, v56
	v_exp_f32_e32 v35, v40
	v_exp_f32_e32 v32, v57
	v_exp_f32_e32 v34, v41
	v_exp_f32_e32 v49, v58
	v_exp_f32_e32 v37, v42
	v_exp_f32_e32 v48, v59
	v_exp_f32_e32 v36, v43
	v_pk_add_f32 v[38:39], v[34:35], v[32:33]
	v_exp_f32_e32 v51, v60
	v_add_f32_e32 v39, v39, v50
	v_add_f32_e32 v40, v38, v39
	v_pk_add_f32 v[38:39], v[36:37], v[48:49]
	v_exp_f32_e32 v50, v61
	v_add_f32_e32 v39, v39, v40
	v_add_f32_e32 v56, v38, v39
	v_exp_f32_e32 v39, v44
	v_exp_f32_e32 v38, v45
	v_exp_f32_e32 v53, v62
	v_exp_f32_e32 v41, v46
	v_exp_f32_e32 v52, v63
	v_exp_f32_e32 v40, v47
	v_pk_add_f32 v[42:43], v[38:39], v[50:51]
	s_nop 0
	v_add_f32_e32 v43, v43, v56
	v_add_f32_e32 v44, v42, v43
	v_pk_add_f32 v[42:43], v[40:41], v[52:53]
	s_nop 0
	v_add_f32_e32 v43, v43, v44
	v_add_f32_e32 v42, v42, v43
	v_add_f32_e32 v56, v140, v42
	v_pk_mov_b32 v[32:33], v[32:33], v[32:33] op_sel:[1,0]
	v_pk_mov_b32 v[34:35], v[34:35], v[34:35] op_sel:[1,0]
	v_pk_mov_b32 v[36:37], v[36:37], v[36:37] op_sel:[1,0]
	v_cvt_pk_bf16_f32 v42, v32, v33
	v_pk_mov_b32 v[32:33], v[48:49], v[48:49] op_sel:[1,0]
	v_cvt_pk_bf16_f32 v34, v34, v35
	v_cvt_pk_bf16_f32 v35, v36, v37
	v_pk_mov_b32 v[36:37], v[38:39], v[38:39] op_sel:[1,0]
	v_pk_mov_b32 v[38:39], v[40:41], v[40:41] op_sel:[1,0]
	v_cvt_pk_bf16_f32 v43, v32, v33
	v_pk_mov_b32 v[32:33], v[50:51], v[50:51] op_sel:[1,0]
	v_cvt_pk_bf16_f32 v36, v36, v37
	v_cvt_pk_bf16_f32 v37, v38, v39
	v_cvt_pk_bf16_f32 v38, v65, v67
	v_cvt_pk_bf16_f32 v39, v69, v71
	v_cvt_pk_bf16_f32 v44, v32, v33
	v_pk_mov_b32 v[32:33], v[52:53], v[52:53] op_sel:[1,0]
	v_cvt_pk_bf16_f32 v40, v73, v75
	v_cvt_pk_bf16_f32 v41, v76, v77
	v_cvt_pk_bf16_f32 v45, v32, v33
	v_cvt_pk_bf16_f32 v46, v64, v66
	v_cvt_pk_bf16_f32 v47, v68, v70
	v_cvt_pk_bf16_f32 v48, v72, v74
	v_cvt_pk_bf16_f32 v49, v54, v55
	s_setprio 1
	s_cmp_lg_u32 s98, 0
	s_cbranch_scc1 .Lstg_y_16
	s_waitcnt lgkmcnt(0)
	s_barrier

	.amdhsa_kernel _Z10fwd_kernel4Args
		.amdhsa_group_segment_fixed_size 0
		.amdhsa_private_segment_fixed_size 0
		.amdhsa_kernarg_size 424
		.amdhsa_user_sgpr_count 2
		.amdhsa_user_sgpr_dispatch_ptr 0
		.amdhsa_user_sgpr_queue_ptr 0
		.amdhsa_user_sgpr_kernarg_segment_ptr 1
		.amdhsa_user_sgpr_dispatch_id 0
		.amdhsa_user_sgpr_kernarg_preload_length 0
		.amdhsa_user_sgpr_kernarg_preload_offset 0
		.amdhsa_user_sgpr_private_segment_size 0
		.amdhsa_uses_dynamic_stack 0
		.amdhsa_enable_private_segment 0
		.amdhsa_system_sgpr_workgroup_id_x 1
		.amdhsa_system_sgpr_workgroup_id_y 0
		.amdhsa_system_sgpr_workgroup_id_z 0
		.amdhsa_system_sgpr_workgroup_info 0
		.amdhsa_system_vgpr_workitem_id 2
		.amdhsa_next_free_vgpr 243
		.amdhsa_next_free_sgpr 101
		.amdhsa_accum_offset 244
		.amdhsa_reserve_vcc 1
		.amdhsa_float_round_mode_32 0
		.amdhsa_float_round_mode_16_64 0
		.amdhsa_float_denorm_mode_32 3
		.amdhsa_float_denorm_mode_16_64 3
		.amdhsa_dx10_clamp 1
		.amdhsa_ieee_mode 1
		.amdhsa_fp16_overflow 0
		.amdhsa_tg_split 0
		.amdhsa_exception_fp_ieee_invalid_op 0
		.amdhsa_exception_fp_denorm_src 0
		.amdhsa_exception_fp_ieee_div_zero 0
		.amdhsa_exception_fp_ieee_overflow 0
		.amdhsa_exception_fp_ieee_underflow 0
		.amdhsa_exception_fp_ieee_inexact 0
		.amdhsa_exception_int_div_zero 0
	.end_amdhsa_kernel

amdhsa.kernels:
  - .agpr_count:     0
    .args:
      - .offset:         0
        .size:           168
        .value_kind:     by_value
      - .offset:         168
        .size:           4
        .value_kind:     hidden_block_count_x
      - .offset:         172
        .size:           4
        .value_kind:     hidden_block_count_y
      - .offset:         176
        .size:           4
        .value_kind:     hidden_block_count_z
      - .offset:         180
        .size:           2
        .value_kind:     hidden_group_size_x
      - .offset:         182
        .size:           2
        .value_kind:     hidden_group_size_y
      - .offset:         184
        .size:           2
        .value_kind:     hidden_group_size_z
      - .offset:         186
        .size:           2
        .value_kind:     hidden_remainder_x
      - .offset:         188
        .size:           2
        .value_kind:     hidden_remainder_y
      - .offset:         190
        .size:           2
        .value_kind:     hidden_remainder_z
      - .offset:         208
        .size:           8
        .value_kind:     hidden_global_offset_x
      - .offset:         216
        .size:           8
        .value_kind:     hidden_global_offset_y
      - .offset:         224
        .size:           8
        .value_kind:     hidden_global_offset_z
      - .offset:         232
        .size:           2
        .value_kind:     hidden_grid_dims
      - .offset:         256
        .size:           8
        .value_kind:     hidden_multigrid_sync_arg
      - .offset:         288
        .size:           4
        .value_kind:     hidden_dynamic_lds_size
    .group_segment_fixed_size: 0
    .kernarg_segment_align: 8
    .kernarg_segment_size: 424
    .language:       OpenCL C
    .language_version:
      - 2
      - 0
    .max_flat_workgroup_size: 512
    .name:           _Z10fwd_kernel4Args
    .private_segment_fixed_size: 0
    .sgpr_count:     107
    .sgpr_spill_count: 52
    .symbol:         _Z10fwd_kernel4Args.kd
    .uniform_work_group_size: 1
    .uses_dynamic_stack: false
    .vgpr_count:     243
    .vgpr_spill_count: 0
    .wavefront_size: 64
